# v62 + the six GEMM K-loop heads aligned to 64 bytes (.p2align 6; placement only, no instruction change)
# speedup vs baseline: 1.0107x; 1.0107x over previous
.LBB0_179:
	s_ashr_i32 s47, s46, 31
	s_lshl_b64 s[48:49], s[46:47], 19
	s_add_u32 s48, s26, s48
	s_addc_u32 s49, s27, s49
	s_and_b64 s[50:51], s[44:45], exec
	s_cselect_b32 s47, s49, s63
	s_cselect_b32 s82, s48, s62
	s_ashr_i32 s21, s20, 31
	s_lshl_b64 s[50:51], s[20:21], 19
	s_add_u32 s50, s59, s50
	s_addc_u32 s51, s66, s51
	s_and_b64 s[84:85], s[44:45], exec
	s_cselect_b32 s21, s51, s61
	s_cselect_b32 s83, s50, s60
	s_add_u32 s89, s60, 0x100
	s_addc_u32 s84, s61, 0
	s_add_u32 s60, s62, 0x40080
	s_addc_u32 s61, s63, 0
	s_mov_b32 s85, -2
	s_add_u32 s62, s60, 0xfffc0080
	s_addc_u32 s63, s61, -1
	s_cmp_eq_u32 s85, 12
	s_cselect_b32 vcc_hi, s47, s63
	s_cselect_b32 vcc_lo, s82, s62
	s_cselect_b32 s63, s21, s84
	s_cselect_b32 s62, s83, s89
	v_lshl_add_u64 v[142:143], s[60:61], 0, v[136:137]
	s_add_i32 m0, s68, 0xc000
	global_load_lds_dwordx4 v[142:143], off
	v_lshl_add_u64 v[142:143], s[60:61], 0, v[134:135]
	s_add_i32 m0, s68, 0xe000
	s_nop 0
	global_load_lds_dwordx4 v[142:143], off
	s_waitcnt vmcnt(8)
	s_waitcnt lgkmcnt(0)
	s_barrier
	s_setprio 1
	s_waitcnt lgkmcnt(0)
	v_mfma_f32_16x16x32_bf16 v[124:127], v[138:141], v[210:213], 0
	v_mfma_f32_16x16x32_bf16 v[116:119], v[176:179], v[210:213], 0
	v_mfma_f32_16x16x32_bf16 v[108:111], v[138:141], v[218:221], 0
	v_mfma_f32_16x16x32_bf16 v[100:103], v[176:179], v[218:221], 0
	v_mfma_f32_16x16x32_bf16 v[92:95], v[138:141], v[228:231], 0
	v_mfma_f32_16x16x32_bf16 v[84:87], v[176:179], v[228:231], 0
	v_mfma_f32_16x16x32_bf16 v[76:79], v[138:141], v[236:239], 0
	v_mfma_f32_16x16x32_bf16 v[68:71], v[176:179], v[236:239], 0
	v_mfma_f32_16x16x32_bf16 v[124:127], v[172:175], v[214:217], v[124:127]
	v_mfma_f32_16x16x32_bf16 v[116:119], v[180:183], v[214:217], v[116:119]
	v_mfma_f32_16x16x32_bf16 v[108:111], v[172:175], v[224:227], v[108:111]
	v_mfma_f32_16x16x32_bf16 v[100:103], v[180:183], v[224:227], v[100:103]
	v_mfma_f32_16x16x32_bf16 v[92:95], v[172:175], v[232:235], v[92:95]
	v_mfma_f32_16x16x32_bf16 v[84:87], v[180:183], v[232:235], v[84:87]
	v_mfma_f32_16x16x32_bf16 v[76:79], v[172:175], v[240:243], v[76:79]
	v_mfma_f32_16x16x32_bf16 v[68:71], v[180:183], v[240:243], v[68:71]
	s_setprio 0
	s_setprio 1
	v_mfma_f32_16x16x32_bf16 v[120:123], v[184:187], v[210:213], 0
	v_mfma_f32_16x16x32_bf16 v[112:115], v[192:195], v[210:213], 0
	v_mfma_f32_16x16x32_bf16 v[104:107], v[184:187], v[218:221], 0
	v_mfma_f32_16x16x32_bf16 v[96:99], v[192:195], v[218:221], 0
	v_mfma_f32_16x16x32_bf16 v[88:91], v[184:187], v[228:231], 0
	v_mfma_f32_16x16x32_bf16 v[80:83], v[192:195], v[228:231], 0
	v_mfma_f32_16x16x32_bf16 v[72:75], v[184:187], v[236:239], 0
	v_mfma_f32_16x16x32_bf16 v[64:67], v[192:195], v[236:239], 0
	v_mfma_f32_16x16x32_bf16 v[120:123], v[188:191], v[214:217], v[120:123]
	v_mfma_f32_16x16x32_bf16 v[112:115], v[196:199], v[214:217], v[112:115]
	v_mfma_f32_16x16x32_bf16 v[104:107], v[188:191], v[224:227], v[104:107]
	v_mfma_f32_16x16x32_bf16 v[96:99], v[196:199], v[224:227], v[96:99]
	v_mfma_f32_16x16x32_bf16 v[88:91], v[188:191], v[232:235], v[88:91]
	v_mfma_f32_16x16x32_bf16 v[80:83], v[196:199], v[232:235], v[80:83]
	v_mfma_f32_16x16x32_bf16 v[72:75], v[188:191], v[240:243], v[72:75]
	v_mfma_f32_16x16x32_bf16 v[64:67], v[196:199], v[240:243], v[64:67]
	s_setprio 0
	s_barrier
	s_add_i32 s86, s86, s67
	v_lshl_add_u64 v[142:143], s[62:63], 0, v[152:153]
	s_mov_b32 m0, s86
	ds_read_b128 v[210:213], v148 offset:16384
	ds_read_b128 v[214:217], v148 offset:17408
	ds_read_b128 v[218:221], v148 offset:18432
	ds_read_b128 v[224:227], v148 offset:19456
	ds_read_b128 v[228:231], v148 offset:20480
	ds_read_b128 v[232:235], v148 offset:21504
	ds_read_b128 v[236:239], v148 offset:22528
	ds_read_b128 v[240:243], v148 offset:23552
	global_load_lds_dwordx4 v[142:143], off
	s_add_i32 m0, s86, 0x2000
	s_add_u32 s86, s62, 0x40000
	v_lshl_add_u64 v[150:151], s[62:63], 0, v[128:129]
	s_addc_u32 s87, s63, 0
	s_add_i32 s92, s92, s67
	global_load_lds_dwordx4 v[150:151], off
	v_lshl_add_u64 v[244:245], s[86:87], 0, v[152:153]
	s_mov_b32 m0, s92
	v_lshl_add_u64 v[246:247], vcc, 0, v[130:131]
	global_load_lds_dwordx4 v[244:245], off
	v_lshl_add_u64 v[244:245], s[86:87], 0, v[128:129]
	s_add_i32 m0, s92, 0x2000
	s_nop 0
	global_load_lds_dwordx4 v[244:245], off
	v_lshl_add_u64 v[244:245], vcc, 0, v[132:133]
	s_mov_b32 m0, s68
	s_nop 0
	global_load_lds_dwordx4 v[244:245], off
	s_mov_b32 m0, s69
	s_nop 0
	global_load_lds_dwordx4 v[246:247], off
	s_waitcnt vmcnt(8)
	s_waitcnt lgkmcnt(0)
	s_barrier
	s_setprio 1
	s_waitcnt lgkmcnt(0)
	v_mfma_f32_16x16x32_bf16 v[60:63], v[138:141], v[210:213], 0
	v_mfma_f32_16x16x32_bf16 v[52:55], v[176:179], v[210:213], 0
	v_mfma_f32_16x16x32_bf16 v[44:47], v[138:141], v[218:221], 0
	v_mfma_f32_16x16x32_bf16 v[36:39], v[176:179], v[218:221], 0
	v_mfma_f32_16x16x32_bf16 v[28:31], v[138:141], v[228:231], 0
	v_mfma_f32_16x16x32_bf16 v[20:23], v[176:179], v[228:231], 0
	v_mfma_f32_16x16x32_bf16 v[12:15], v[138:141], v[236:239], 0
	v_mfma_f32_16x16x32_bf16 v[4:7], v[176:179], v[236:239], 0
	v_mfma_f32_16x16x32_bf16 v[60:63], v[172:175], v[214:217], v[60:63]
	v_mfma_f32_16x16x32_bf16 v[52:55], v[180:183], v[214:217], v[52:55]
	v_mfma_f32_16x16x32_bf16 v[44:47], v[172:175], v[224:227], v[44:47]
	v_mfma_f32_16x16x32_bf16 v[36:39], v[180:183], v[224:227], v[36:39]
	v_mfma_f32_16x16x32_bf16 v[28:31], v[172:175], v[232:235], v[28:31]
	v_mfma_f32_16x16x32_bf16 v[20:23], v[180:183], v[232:235], v[20:23]
	v_mfma_f32_16x16x32_bf16 v[12:15], v[172:175], v[240:243], v[12:15]
	v_mfma_f32_16x16x32_bf16 v[4:7], v[180:183], v[240:243], v[4:7]
	s_setprio 0
	s_setprio 1
	v_mfma_f32_16x16x32_bf16 v[56:59], v[184:187], v[210:213], 0
	v_mfma_f32_16x16x32_bf16 v[48:51], v[192:195], v[210:213], 0
	v_mfma_f32_16x16x32_bf16 v[40:43], v[184:187], v[218:221], 0
	v_mfma_f32_16x16x32_bf16 v[32:35], v[192:195], v[218:221], 0
	v_mfma_f32_16x16x32_bf16 v[24:27], v[184:187], v[228:231], 0
	v_mfma_f32_16x16x32_bf16 v[16:19], v[192:195], v[228:231], 0
	v_mfma_f32_16x16x32_bf16 v[8:11], v[184:187], v[236:239], 0
	v_mfma_f32_16x16x32_bf16 v[0:3], v[192:195], v[236:239], 0
	v_mfma_f32_16x16x32_bf16 v[56:59], v[188:191], v[214:217], v[56:59]
	v_mfma_f32_16x16x32_bf16 v[48:51], v[196:199], v[214:217], v[48:51]
	v_mfma_f32_16x16x32_bf16 v[40:43], v[188:191], v[224:227], v[40:43]
	v_mfma_f32_16x16x32_bf16 v[32:35], v[196:199], v[224:227], v[32:35]
	v_mfma_f32_16x16x32_bf16 v[24:27], v[188:191], v[232:235], v[24:27]
	v_mfma_f32_16x16x32_bf16 v[16:19], v[196:199], v[232:235], v[16:19]
	v_mfma_f32_16x16x32_bf16 v[8:11], v[188:191], v[240:243], v[8:11]
	v_mfma_f32_16x16x32_bf16 v[0:3], v[196:199], v[240:243], v[0:3]
	s_setprio 0
	s_barrier
	s_add_i32 s92, 0, 0x18000
	v_add_u32_e32 v149, s92, v145
	s_add_i32 s93, 0, 0x1c000
	ds_read_b128 v[138:141], v149
	ds_read_b128 v[172:175], v149 offset:1024
	ds_read_b128 v[176:179], v149 offset:2048
	ds_read_b128 v[180:183], v149 offset:3072
	v_add_u32_e32 v149, s93, v145
	ds_read_b128 v[184:187], v149
	ds_read_b128 v[188:191], v149 offset:1024
	ds_read_b128 v[192:195], v149 offset:2048
	ds_read_b128 v[196:199], v149 offset:3072
	s_add_u32 s86, vcc_lo, 0x40000
	s_addc_u32 s87, vcc_hi, 0
	s_mov_b32 m0, s74
	v_lshl_add_u64 v[248:249], s[86:87], 0, v[132:133]
	ds_read_b128 v[210:213], v148 offset:32768
	ds_read_b128 v[214:217], v148 offset:33792
	ds_read_b128 v[218:221], v148 offset:34816
	ds_read_b128 v[224:227], v148 offset:35840
	ds_read_b128 v[228:231], v148 offset:36864
	ds_read_b128 v[232:235], v148 offset:37888
	ds_read_b128 v[236:239], v148 offset:38912
	ds_read_b128 v[240:243], v148 offset:39936
	global_load_lds_dwordx4 v[248:249], off
	v_lshl_add_u64 v[248:249], s[86:87], 0, v[130:131]
	s_mov_b32 m0, s75
	s_nop 0
	global_load_lds_dwordx4 v[248:249], off
	s_waitcnt vmcnt(8)
	s_waitcnt lgkmcnt(0)
	s_barrier
	s_setprio 1
	s_waitcnt lgkmcnt(0)
	v_mfma_f32_16x16x32_bf16 v[124:127], v[138:141], v[210:213], v[124:127]
	v_mfma_f32_16x16x32_bf16 v[116:119], v[176:179], v[210:213], v[116:119]
	v_mfma_f32_16x16x32_bf16 v[108:111], v[138:141], v[218:221], v[108:111]
	v_mfma_f32_16x16x32_bf16 v[100:103], v[176:179], v[218:221], v[100:103]
	v_mfma_f32_16x16x32_bf16 v[92:95], v[138:141], v[228:231], v[92:95]
	v_mfma_f32_16x16x32_bf16 v[84:87], v[176:179], v[228:231], v[84:87]
	v_mfma_f32_16x16x32_bf16 v[76:79], v[138:141], v[236:239], v[76:79]
	v_mfma_f32_16x16x32_bf16 v[68:71], v[176:179], v[236:239], v[68:71]
	v_mfma_f32_16x16x32_bf16 v[124:127], v[172:175], v[214:217], v[124:127]
	v_mfma_f32_16x16x32_bf16 v[116:119], v[180:183], v[214:217], v[116:119]
	v_mfma_f32_16x16x32_bf16 v[108:111], v[172:175], v[224:227], v[108:111]
	v_mfma_f32_16x16x32_bf16 v[100:103], v[180:183], v[224:227], v[100:103]
	v_mfma_f32_16x16x32_bf16 v[92:95], v[172:175], v[232:235], v[92:95]
	v_mfma_f32_16x16x32_bf16 v[84:87], v[180:183], v[232:235], v[84:87]
	v_mfma_f32_16x16x32_bf16 v[76:79], v[172:175], v[240:243], v[76:79]
	v_mfma_f32_16x16x32_bf16 v[68:71], v[180:183], v[240:243], v[68:71]
	s_setprio 0
	s_setprio 1
	v_mfma_f32_16x16x32_bf16 v[120:123], v[184:187], v[210:213], v[120:123]
	v_mfma_f32_16x16x32_bf16 v[112:115], v[192:195], v[210:213], v[112:115]
	v_mfma_f32_16x16x32_bf16 v[104:107], v[184:187], v[218:221], v[104:107]
	v_mfma_f32_16x16x32_bf16 v[96:99], v[192:195], v[218:221], v[96:99]
	v_mfma_f32_16x16x32_bf16 v[88:91], v[184:187], v[228:231], v[88:91]
	v_mfma_f32_16x16x32_bf16 v[80:83], v[192:195], v[228:231], v[80:83]
	v_mfma_f32_16x16x32_bf16 v[72:75], v[184:187], v[236:239], v[72:75]
	v_mfma_f32_16x16x32_bf16 v[64:67], v[192:195], v[236:239], v[64:67]
	v_mfma_f32_16x16x32_bf16 v[120:123], v[188:191], v[214:217], v[120:123]
	v_mfma_f32_16x16x32_bf16 v[112:115], v[196:199], v[214:217], v[112:115]
	v_mfma_f32_16x16x32_bf16 v[104:107], v[188:191], v[224:227], v[104:107]
	v_mfma_f32_16x16x32_bf16 v[96:99], v[196:199], v[224:227], v[96:99]
	v_mfma_f32_16x16x32_bf16 v[88:91], v[188:191], v[232:235], v[88:91]
	v_mfma_f32_16x16x32_bf16 v[80:83], v[196:199], v[232:235], v[80:83]
	v_mfma_f32_16x16x32_bf16 v[72:75], v[188:191], v[240:243], v[72:75]
	v_mfma_f32_16x16x32_bf16 v[64:67], v[196:199], v[240:243], v[64:67]
	s_setprio 0
	s_barrier
	s_add_i32 s86, s92, s67
	v_lshl_add_u64 v[142:143], v[142:143], 0, s[22:23]
	s_mov_b32 m0, s86
	ds_read_b128 v[210:213], v148 offset:49152
	ds_read_b128 v[214:217], v148 offset:50176
	ds_read_b128 v[218:221], v148 offset:51200
	ds_read_b128 v[224:227], v148 offset:52224
	ds_read_b128 v[228:231], v148 offset:53248
	ds_read_b128 v[232:235], v148 offset:54272
	ds_read_b128 v[236:239], v148 offset:55296
	ds_read_b128 v[240:243], v148 offset:56320
	global_load_lds_dwordx4 v[142:143], off
	s_add_i32 m0, s86, 0x2000
	s_add_u32 s62, s62, 0x40080
	v_lshl_add_u64 v[142:143], v[150:151], 0, s[22:23]
	s_addc_u32 s63, s63, 0
	s_add_i32 s86, s93, s67
	global_load_lds_dwordx4 v[142:143], off
	v_lshl_add_u64 v[142:143], s[62:63], 0, v[152:153]
	s_mov_b32 m0, s86
	s_nop 0
	global_load_lds_dwordx4 v[142:143], off
	v_lshl_add_u64 v[142:143], s[62:63], 0, v[128:129]
	s_add_i32 m0, s86, 0x2000
	s_nop 0
	global_load_lds_dwordx4 v[142:143], off
	v_lshl_add_u64 v[142:143], v[244:245], 0, s[22:23]
	s_mov_b32 m0, s77
	s_nop 0
	global_load_lds_dwordx4 v[142:143], off
	v_lshl_add_u64 v[142:143], v[246:247], 0, s[22:23]
	s_mov_b32 m0, s78
	s_nop 0
	global_load_lds_dwordx4 v[142:143], off
	s_waitcnt vmcnt(8)
	s_waitcnt lgkmcnt(0)
	s_barrier
	s_setprio 1
	s_waitcnt lgkmcnt(0)
	v_mfma_f32_16x16x32_bf16 v[60:63], v[138:141], v[210:213], v[60:63]
	v_mfma_f32_16x16x32_bf16 v[52:55], v[176:179], v[210:213], v[52:55]
	v_mfma_f32_16x16x32_bf16 v[44:47], v[138:141], v[218:221], v[44:47]
	v_mfma_f32_16x16x32_bf16 v[36:39], v[176:179], v[218:221], v[36:39]
	v_mfma_f32_16x16x32_bf16 v[28:31], v[138:141], v[228:231], v[28:31]
	v_mfma_f32_16x16x32_bf16 v[20:23], v[176:179], v[228:231], v[20:23]
	v_mfma_f32_16x16x32_bf16 v[12:15], v[138:141], v[236:239], v[12:15]
	v_mfma_f32_16x16x32_bf16 v[4:7], v[176:179], v[236:239], v[4:7]
	v_mfma_f32_16x16x32_bf16 v[60:63], v[172:175], v[214:217], v[60:63]
	v_mfma_f32_16x16x32_bf16 v[52:55], v[180:183], v[214:217], v[52:55]
	v_mfma_f32_16x16x32_bf16 v[44:47], v[172:175], v[224:227], v[44:47]
	v_mfma_f32_16x16x32_bf16 v[36:39], v[180:183], v[224:227], v[36:39]
	v_mfma_f32_16x16x32_bf16 v[28:31], v[172:175], v[232:235], v[28:31]
	v_mfma_f32_16x16x32_bf16 v[20:23], v[180:183], v[232:235], v[20:23]
	v_mfma_f32_16x16x32_bf16 v[12:15], v[172:175], v[240:243], v[12:15]
	v_mfma_f32_16x16x32_bf16 v[4:7], v[180:183], v[240:243], v[4:7]
	s_setprio 0
	s_setprio 1
	v_mfma_f32_16x16x32_bf16 v[56:59], v[184:187], v[210:213], v[56:59]
	v_mfma_f32_16x16x32_bf16 v[48:51], v[192:195], v[210:213], v[48:51]
	v_mfma_f32_16x16x32_bf16 v[40:43], v[184:187], v[218:221], v[40:43]
	v_mfma_f32_16x16x32_bf16 v[32:35], v[192:195], v[218:221], v[32:35]
	v_mfma_f32_16x16x32_bf16 v[24:27], v[184:187], v[228:231], v[24:27]
	v_mfma_f32_16x16x32_bf16 v[16:19], v[192:195], v[228:231], v[16:19]
	v_mfma_f32_16x16x32_bf16 v[8:11], v[184:187], v[236:239], v[8:11]
	v_mfma_f32_16x16x32_bf16 v[0:3], v[192:195], v[236:239], v[0:3]
	v_mfma_f32_16x16x32_bf16 v[56:59], v[188:191], v[214:217], v[56:59]
	v_mfma_f32_16x16x32_bf16 v[48:51], v[196:199], v[214:217], v[48:51]
	v_mfma_f32_16x16x32_bf16 v[40:43], v[188:191], v[224:227], v[40:43]
	v_mfma_f32_16x16x32_bf16 v[32:35], v[196:199], v[224:227], v[32:35]
	v_mfma_f32_16x16x32_bf16 v[24:27], v[188:191], v[232:235], v[24:27]
	v_mfma_f32_16x16x32_bf16 v[16:19], v[196:199], v[232:235], v[16:19]
	v_mfma_f32_16x16x32_bf16 v[8:11], v[188:191], v[240:243], v[8:11]
	v_mfma_f32_16x16x32_bf16 v[0:3], v[196:199], v[240:243], v[0:3]
	s_setprio 0
	s_barrier
	s_add_i32 s85, s85, 2
	s_add_u32 s89, s89, 0x100
	s_addc_u32 s84, s84, 0
	s_add_u32 s60, s60, 0x100
	s_addc_u32 s61, s61, 0
	s_cmp_gt_u32 s85, 13
	.p2align	6

.LBB0_280:
	s_add_u32 s84, s18, 0x100
	s_addc_u32 s85, s19, 0
	s_mov_b32 s86, -2
	s_add_u32 vcc_lo, s60, 0x100
	s_addc_u32 vcc_hi, s61, 0
	s_cmp_eq_u32 s86, 40
	s_cselect_b32 s67, s51, vcc_hi
	s_cselect_b32 s66, s50, vcc_lo
	s_cselect_b32 s19, s45, s85
	s_cselect_b32 s18, s44, s84
	v_lshl_add_u64 v[198:199], s[60:61], 0, v[180:181]
	s_add_i32 m0, s69, 0xc000
	global_load_lds_dwordx4 v[198:199], off
	v_lshl_add_u64 v[198:199], s[60:61], 0, v[178:179]
	s_add_i32 m0, s69, 0xe000
	s_nop 0
	global_load_lds_dwordx4 v[198:199], off
	s_waitcnt vmcnt(8)
	s_waitcnt lgkmcnt(0)
	s_barrier
	s_setprio 1
	s_waitcnt lgkmcnt(0)
	v_mfma_f32_16x16x32_bf16 v[124:127], v[128:131], v[190:193], 0
	v_mfma_f32_16x16x32_bf16 v[120:123], v[136:139], v[190:193], 0
	v_mfma_f32_16x16x32_bf16 v[108:111], v[128:131], v[214:217], 0
	v_mfma_f32_16x16x32_bf16 v[104:107], v[136:139], v[214:217], 0
	v_mfma_f32_16x16x32_bf16 v[92:95], v[128:131], v[224:227], 0
	v_mfma_f32_16x16x32_bf16 v[88:91], v[136:139], v[224:227], 0
	v_mfma_f32_16x16x32_bf16 v[76:79], v[128:131], v[232:235], 0
	v_mfma_f32_16x16x32_bf16 v[72:75], v[136:139], v[232:235], 0
	v_mfma_f32_16x16x32_bf16 v[124:127], v[132:135], v[194:197], v[124:127]
	v_mfma_f32_16x16x32_bf16 v[120:123], v[140:143], v[194:197], v[120:123]
	v_mfma_f32_16x16x32_bf16 v[108:111], v[132:135], v[218:221], v[108:111]
	v_mfma_f32_16x16x32_bf16 v[104:107], v[140:143], v[218:221], v[104:107]
	v_mfma_f32_16x16x32_bf16 v[92:95], v[132:135], v[228:231], v[92:95]
	v_mfma_f32_16x16x32_bf16 v[88:91], v[140:143], v[228:231], v[88:91]
	v_mfma_f32_16x16x32_bf16 v[76:79], v[132:135], v[236:239], v[76:79]
	v_mfma_f32_16x16x32_bf16 v[72:75], v[140:143], v[236:239], v[72:75]
	s_setprio 0
	s_setprio 1
	v_mfma_f32_16x16x32_bf16 v[116:119], v[144:147], v[190:193], 0
	v_mfma_f32_16x16x32_bf16 v[112:115], v[182:185], v[190:193], 0
	v_mfma_f32_16x16x32_bf16 v[100:103], v[144:147], v[214:217], 0
	v_mfma_f32_16x16x32_bf16 v[96:99], v[182:185], v[214:217], 0
	v_mfma_f32_16x16x32_bf16 v[84:87], v[144:147], v[224:227], 0
	v_mfma_f32_16x16x32_bf16 v[80:83], v[182:185], v[224:227], 0
	v_mfma_f32_16x16x32_bf16 v[68:71], v[144:147], v[232:235], 0
	v_mfma_f32_16x16x32_bf16 v[64:67], v[182:185], v[232:235], 0
	v_mfma_f32_16x16x32_bf16 v[116:119], v[148:151], v[194:197], v[116:119]
	v_mfma_f32_16x16x32_bf16 v[112:115], v[186:189], v[194:197], v[112:115]
	v_mfma_f32_16x16x32_bf16 v[100:103], v[148:151], v[218:221], v[100:103]
	v_mfma_f32_16x16x32_bf16 v[96:99], v[186:189], v[218:221], v[96:99]
	v_mfma_f32_16x16x32_bf16 v[84:87], v[148:151], v[228:231], v[84:87]
	v_mfma_f32_16x16x32_bf16 v[80:83], v[186:189], v[228:231], v[80:83]
	v_mfma_f32_16x16x32_bf16 v[68:71], v[148:151], v[236:239], v[68:71]
	v_mfma_f32_16x16x32_bf16 v[64:67], v[186:189], v[236:239], v[64:67]
	s_setprio 0
	s_barrier
	s_add_i32 s60, s87, s68
	v_lshl_add_u64 v[198:199], s[18:19], 0, v[152:153]
	s_mov_b32 m0, s60
	ds_read_b128 v[190:193], v212 offset:16384
	ds_read_b128 v[194:197], v212 offset:17408
	ds_read_b128 v[214:217], v212 offset:18432
	ds_read_b128 v[218:221], v212 offset:19456
	ds_read_b128 v[224:227], v212 offset:20480
	ds_read_b128 v[228:231], v212 offset:21504
	ds_read_b128 v[232:235], v212 offset:22528
	ds_read_b128 v[236:239], v212 offset:23552
	global_load_lds_dwordx4 v[198:199], off
	s_add_i32 m0, s60, 0x2000
	s_add_u32 s60, s18, 0xb0000
	v_lshl_add_u64 v[240:241], s[18:19], 0, v[172:173]
	s_addc_u32 s61, s19, 0
	s_add_i32 s87, s92, s68
	global_load_lds_dwordx4 v[240:241], off
	v_lshl_add_u64 v[242:243], s[60:61], 0, v[152:153]
	s_mov_b32 m0, s87
	v_lshl_add_u64 v[244:245], s[66:67], 0, v[174:175]
	global_load_lds_dwordx4 v[242:243], off
	v_lshl_add_u64 v[242:243], s[60:61], 0, v[172:173]
	s_add_i32 m0, s87, 0x2000
	s_nop 0
	global_load_lds_dwordx4 v[242:243], off
	v_lshl_add_u64 v[242:243], s[66:67], 0, v[176:177]
	s_mov_b32 m0, s69
	s_nop 0
	global_load_lds_dwordx4 v[242:243], off
	s_mov_b32 m0, s74
	s_nop 0
	global_load_lds_dwordx4 v[244:245], off
	s_waitcnt vmcnt(8)
	s_waitcnt lgkmcnt(0)
	s_barrier
	s_setprio 1
	s_waitcnt lgkmcnt(0)
	v_mfma_f32_16x16x32_bf16 v[60:63], v[128:131], v[190:193], 0
	v_mfma_f32_16x16x32_bf16 v[56:59], v[136:139], v[190:193], 0
	v_mfma_f32_16x16x32_bf16 v[44:47], v[128:131], v[214:217], 0
	v_mfma_f32_16x16x32_bf16 v[40:43], v[136:139], v[214:217], 0
	v_mfma_f32_16x16x32_bf16 v[28:31], v[128:131], v[224:227], 0
	v_mfma_f32_16x16x32_bf16 v[24:27], v[136:139], v[224:227], 0
	v_mfma_f32_16x16x32_bf16 v[12:15], v[128:131], v[232:235], 0
	v_mfma_f32_16x16x32_bf16 v[8:11], v[136:139], v[232:235], 0
	v_mfma_f32_16x16x32_bf16 v[60:63], v[132:135], v[194:197], v[60:63]
	v_mfma_f32_16x16x32_bf16 v[56:59], v[140:143], v[194:197], v[56:59]
	v_mfma_f32_16x16x32_bf16 v[44:47], v[132:135], v[218:221], v[44:47]
	v_mfma_f32_16x16x32_bf16 v[40:43], v[140:143], v[218:221], v[40:43]
	v_mfma_f32_16x16x32_bf16 v[28:31], v[132:135], v[228:231], v[28:31]
	v_mfma_f32_16x16x32_bf16 v[24:27], v[140:143], v[228:231], v[24:27]
	v_mfma_f32_16x16x32_bf16 v[12:15], v[132:135], v[236:239], v[12:15]
	v_mfma_f32_16x16x32_bf16 v[8:11], v[140:143], v[236:239], v[8:11]
	s_setprio 0
	s_setprio 1
	v_mfma_f32_16x16x32_bf16 v[52:55], v[144:147], v[190:193], 0
	v_mfma_f32_16x16x32_bf16 v[48:51], v[182:185], v[190:193], 0
	v_mfma_f32_16x16x32_bf16 v[36:39], v[144:147], v[214:217], 0
	v_mfma_f32_16x16x32_bf16 v[32:35], v[182:185], v[214:217], 0
	v_mfma_f32_16x16x32_bf16 v[20:23], v[144:147], v[224:227], 0
	v_mfma_f32_16x16x32_bf16 v[16:19], v[182:185], v[224:227], 0
	v_mfma_f32_16x16x32_bf16 v[4:7], v[144:147], v[232:235], 0
	v_mfma_f32_16x16x32_bf16 v[0:3], v[182:185], v[232:235], 0
	v_mfma_f32_16x16x32_bf16 v[52:55], v[148:151], v[194:197], v[52:55]
	v_mfma_f32_16x16x32_bf16 v[48:51], v[186:189], v[194:197], v[48:51]
	v_mfma_f32_16x16x32_bf16 v[36:39], v[148:151], v[218:221], v[36:39]
	v_mfma_f32_16x16x32_bf16 v[32:35], v[186:189], v[218:221], v[32:35]
	v_mfma_f32_16x16x32_bf16 v[20:23], v[148:151], v[228:231], v[20:23]
	v_mfma_f32_16x16x32_bf16 v[16:19], v[186:189], v[228:231], v[16:19]
	v_mfma_f32_16x16x32_bf16 v[4:7], v[148:151], v[236:239], v[4:7]
	v_mfma_f32_16x16x32_bf16 v[0:3], v[186:189], v[236:239], v[0:3]
	s_setprio 0
	s_barrier
	s_add_i32 s87, 0, 0x18000
	s_add_i32 s92, 0, 0x1c000
	v_add_u32_e32 v140, s87, v210
	v_add_u32_e32 v186, s92, v210
	ds_read_b128 v[128:131], v140
	ds_read_b128 v[132:135], v140 offset:1024
	ds_read_b128 v[136:139], v140 offset:2048
	ds_read_b128 v[140:143], v140 offset:3072
	ds_read_b128 v[144:147], v186
	ds_read_b128 v[148:151], v186 offset:1024
	ds_read_b128 v[182:185], v186 offset:2048
	ds_read_b128 v[186:189], v186 offset:3072
	s_add_u32 s60, s66, 0xb0000
	s_addc_u32 s61, s67, 0
	s_mov_b32 m0, s75
	v_lshl_add_u64 v[246:247], s[60:61], 0, v[176:177]
	ds_read_b128 v[190:193], v212 offset:32768
	ds_read_b128 v[194:197], v212 offset:33792
	ds_read_b128 v[214:217], v212 offset:34816
	ds_read_b128 v[218:221], v212 offset:35840
	ds_read_b128 v[224:227], v212 offset:36864
	ds_read_b128 v[228:231], v212 offset:37888
	ds_read_b128 v[232:235], v212 offset:38912
	ds_read_b128 v[236:239], v212 offset:39936
	global_load_lds_dwordx4 v[246:247], off
	v_lshl_add_u64 v[246:247], s[60:61], 0, v[174:175]
	s_mov_b32 m0, s76
	s_nop 0
	global_load_lds_dwordx4 v[246:247], off
	s_waitcnt vmcnt(8)
	s_waitcnt lgkmcnt(0)
	s_barrier
	s_setprio 1
	s_waitcnt lgkmcnt(0)
	v_mfma_f32_16x16x32_bf16 v[124:127], v[128:131], v[190:193], v[124:127]
	v_mfma_f32_16x16x32_bf16 v[120:123], v[136:139], v[190:193], v[120:123]
	v_mfma_f32_16x16x32_bf16 v[108:111], v[128:131], v[214:217], v[108:111]
	v_mfma_f32_16x16x32_bf16 v[104:107], v[136:139], v[214:217], v[104:107]
	v_mfma_f32_16x16x32_bf16 v[92:95], v[128:131], v[224:227], v[92:95]
	v_mfma_f32_16x16x32_bf16 v[88:91], v[136:139], v[224:227], v[88:91]
	v_mfma_f32_16x16x32_bf16 v[76:79], v[128:131], v[232:235], v[76:79]
	v_mfma_f32_16x16x32_bf16 v[72:75], v[136:139], v[232:235], v[72:75]
	v_mfma_f32_16x16x32_bf16 v[124:127], v[132:135], v[194:197], v[124:127]
	v_mfma_f32_16x16x32_bf16 v[120:123], v[140:143], v[194:197], v[120:123]
	v_mfma_f32_16x16x32_bf16 v[108:111], v[132:135], v[218:221], v[108:111]
	v_mfma_f32_16x16x32_bf16 v[104:107], v[140:143], v[218:221], v[104:107]
	v_mfma_f32_16x16x32_bf16 v[92:95], v[132:135], v[228:231], v[92:95]
	v_mfma_f32_16x16x32_bf16 v[88:91], v[140:143], v[228:231], v[88:91]
	v_mfma_f32_16x16x32_bf16 v[76:79], v[132:135], v[236:239], v[76:79]
	v_mfma_f32_16x16x32_bf16 v[72:75], v[140:143], v[236:239], v[72:75]
	s_setprio 0
	s_setprio 1
	v_mfma_f32_16x16x32_bf16 v[116:119], v[144:147], v[190:193], v[116:119]
	v_mfma_f32_16x16x32_bf16 v[112:115], v[182:185], v[190:193], v[112:115]
	v_mfma_f32_16x16x32_bf16 v[100:103], v[144:147], v[214:217], v[100:103]
	v_mfma_f32_16x16x32_bf16 v[96:99], v[182:185], v[214:217], v[96:99]
	v_mfma_f32_16x16x32_bf16 v[84:87], v[144:147], v[224:227], v[84:87]
	v_mfma_f32_16x16x32_bf16 v[80:83], v[182:185], v[224:227], v[80:83]
	v_mfma_f32_16x16x32_bf16 v[68:71], v[144:147], v[232:235], v[68:71]
	v_mfma_f32_16x16x32_bf16 v[64:67], v[182:185], v[232:235], v[64:67]
	v_mfma_f32_16x16x32_bf16 v[116:119], v[148:151], v[194:197], v[116:119]
	v_mfma_f32_16x16x32_bf16 v[112:115], v[186:189], v[194:197], v[112:115]
	v_mfma_f32_16x16x32_bf16 v[100:103], v[148:151], v[218:221], v[100:103]
	v_mfma_f32_16x16x32_bf16 v[96:99], v[186:189], v[218:221], v[96:99]
	v_mfma_f32_16x16x32_bf16 v[84:87], v[148:151], v[228:231], v[84:87]
	v_mfma_f32_16x16x32_bf16 v[80:83], v[186:189], v[228:231], v[80:83]
	v_mfma_f32_16x16x32_bf16 v[68:71], v[148:151], v[236:239], v[68:71]
	v_mfma_f32_16x16x32_bf16 v[64:67], v[186:189], v[236:239], v[64:67]
	s_setprio 0
	s_barrier
	s_add_i32 s60, s87, s68
	v_lshl_add_u64 v[198:199], v[198:199], 0, s[22:23]
	s_mov_b32 m0, s60
	ds_read_b128 v[190:193], v212 offset:49152
	ds_read_b128 v[194:197], v212 offset:50176
	ds_read_b128 v[214:217], v212 offset:51200
	ds_read_b128 v[218:221], v212 offset:52224
	ds_read_b128 v[224:227], v212 offset:53248
	ds_read_b128 v[228:231], v212 offset:54272
	ds_read_b128 v[232:235], v212 offset:55296
	ds_read_b128 v[236:239], v212 offset:56320
	global_load_lds_dwordx4 v[198:199], off
	s_add_i32 m0, s60, 0x2000
	s_add_u32 s18, s18, 0xb0080
	v_lshl_add_u64 v[198:199], v[240:241], 0, s[22:23]
	s_addc_u32 s19, s19, 0
	s_add_i32 s60, s92, s68
	global_load_lds_dwordx4 v[198:199], off
	v_lshl_add_u64 v[198:199], s[18:19], 0, v[152:153]
	s_mov_b32 m0, s60
	s_nop 0
	global_load_lds_dwordx4 v[198:199], off
	v_lshl_add_u64 v[198:199], s[18:19], 0, v[172:173]
	s_add_i32 m0, s60, 0x2000
	s_nop 0
	global_load_lds_dwordx4 v[198:199], off
	v_lshl_add_u64 v[198:199], v[242:243], 0, s[22:23]
	s_mov_b32 m0, s79
	s_nop 0
	global_load_lds_dwordx4 v[198:199], off
	v_lshl_add_u64 v[198:199], v[244:245], 0, s[22:23]
	s_mov_b32 m0, s80
	s_nop 0
	global_load_lds_dwordx4 v[198:199], off
	s_waitcnt vmcnt(8)
	s_waitcnt lgkmcnt(0)
	s_barrier
	s_setprio 1
	s_waitcnt lgkmcnt(0)
	v_mfma_f32_16x16x32_bf16 v[60:63], v[128:131], v[190:193], v[60:63]
	v_mfma_f32_16x16x32_bf16 v[56:59], v[136:139], v[190:193], v[56:59]
	v_mfma_f32_16x16x32_bf16 v[44:47], v[128:131], v[214:217], v[44:47]
	v_mfma_f32_16x16x32_bf16 v[40:43], v[136:139], v[214:217], v[40:43]
	v_mfma_f32_16x16x32_bf16 v[28:31], v[128:131], v[224:227], v[28:31]
	v_mfma_f32_16x16x32_bf16 v[24:27], v[136:139], v[224:227], v[24:27]
	v_mfma_f32_16x16x32_bf16 v[12:15], v[128:131], v[232:235], v[12:15]
	v_mfma_f32_16x16x32_bf16 v[8:11], v[136:139], v[232:235], v[8:11]
	v_mfma_f32_16x16x32_bf16 v[60:63], v[132:135], v[194:197], v[60:63]
	v_mfma_f32_16x16x32_bf16 v[56:59], v[140:143], v[194:197], v[56:59]
	v_mfma_f32_16x16x32_bf16 v[44:47], v[132:135], v[218:221], v[44:47]
	v_mfma_f32_16x16x32_bf16 v[40:43], v[140:143], v[218:221], v[40:43]
	v_mfma_f32_16x16x32_bf16 v[28:31], v[132:135], v[228:231], v[28:31]
	v_mfma_f32_16x16x32_bf16 v[24:27], v[140:143], v[228:231], v[24:27]
	v_mfma_f32_16x16x32_bf16 v[12:15], v[132:135], v[236:239], v[12:15]
	v_mfma_f32_16x16x32_bf16 v[8:11], v[140:143], v[236:239], v[8:11]
	s_setprio 0
	s_setprio 1
	v_mfma_f32_16x16x32_bf16 v[52:55], v[144:147], v[190:193], v[52:55]
	v_mfma_f32_16x16x32_bf16 v[48:51], v[182:185], v[190:193], v[48:51]
	v_mfma_f32_16x16x32_bf16 v[36:39], v[144:147], v[214:217], v[36:39]
	v_mfma_f32_16x16x32_bf16 v[32:35], v[182:185], v[214:217], v[32:35]
	v_mfma_f32_16x16x32_bf16 v[20:23], v[144:147], v[224:227], v[20:23]
	v_mfma_f32_16x16x32_bf16 v[16:19], v[182:185], v[224:227], v[16:19]
	v_mfma_f32_16x16x32_bf16 v[4:7], v[144:147], v[232:235], v[4:7]
	v_mfma_f32_16x16x32_bf16 v[0:3], v[182:185], v[232:235], v[0:3]
	v_mfma_f32_16x16x32_bf16 v[52:55], v[148:151], v[194:197], v[52:55]
	v_mfma_f32_16x16x32_bf16 v[48:51], v[186:189], v[194:197], v[48:51]
	v_mfma_f32_16x16x32_bf16 v[36:39], v[148:151], v[218:221], v[36:39]
	v_mfma_f32_16x16x32_bf16 v[32:35], v[186:189], v[218:221], v[32:35]
	v_mfma_f32_16x16x32_bf16 v[20:23], v[148:151], v[228:231], v[20:23]
	v_mfma_f32_16x16x32_bf16 v[16:19], v[186:189], v[228:231], v[16:19]
	v_mfma_f32_16x16x32_bf16 v[4:7], v[148:151], v[236:239], v[4:7]
	v_mfma_f32_16x16x32_bf16 v[0:3], v[186:189], v[236:239], v[0:3]
	s_setprio 0
	s_barrier
	s_add_i32 s86, s86, 2
	s_add_u32 s84, s84, 0x100
	s_addc_u32 s85, s85, 0
	s_cmp_gt_u32 s86, 41
	s_mov_b64 s[60:61], vcc
	.p2align	6

.LBB0_418:
	s_ashr_i32 s21, s20, 31
	s_lshl_b64 s[50:51], s[20:21], 19
	s_add_u32 s50, s26, s50
	s_addc_u32 s51, s27, s51
	s_and_b64 s[60:61], s[46:47], exec
	s_cselect_b32 s21, s51, s45
	s_cselect_b32 s78, s50, s44
	s_ashr_i32 s19, s18, 31
	s_lshl_b64 s[60:61], s[18:19], 19
	v_readlane_b32 s19, v254, 42
	s_add_u32 s60, s19, s60
	v_readlane_b32 s19, v254, 43
	s_addc_u32 s61, s19, s61
	s_and_b64 s[62:63], s[46:47], exec
	s_cselect_b32 s19, s61, s49
	s_cselect_b32 s79, s60, s48
	s_add_u32 s80, s48, 0x100
	s_addc_u32 s81, s49, 0
	s_add_u32 s48, s44, 0x40080
	s_addc_u32 s49, s45, 0
	s_mov_b32 s82, -2
	s_add_u32 s44, s48, 0xfffc0080
	s_addc_u32 s45, s49, -1
	s_cmp_eq_u32 s82, 12
	s_cselect_b32 s63, s21, s45
	s_cselect_b32 s62, s78, s44
	s_cselect_b32 s45, s19, s81
	s_cselect_b32 s44, s79, s80
	v_lshl_add_u64 v[182:183], s[48:49], 0, v[172:173]
	s_add_i32 m0, s59, 0xc000
	global_load_lds_dwordx4 v[182:183], off
	v_lshl_add_u64 v[182:183], s[48:49], 0, v[150:151]
	s_add_i32 m0, s59, 0xe000
	s_nop 0
	global_load_lds_dwordx4 v[182:183], off
	s_waitcnt vmcnt(8)
	s_waitcnt lgkmcnt(0)
	s_barrier
	s_setprio 1
	s_waitcnt lgkmcnt(0)
	v_mfma_f32_16x16x32_bf16 v[140:143], v[72:75], v[210:213], 0
	v_mfma_f32_16x16x32_bf16 v[136:139], v[80:83], v[210:213], 0
	v_mfma_f32_16x16x32_bf16 v[124:127], v[72:75], v[218:221], 0
	v_mfma_f32_16x16x32_bf16 v[120:123], v[80:83], v[218:221], 0
	v_mfma_f32_16x16x32_bf16 v[108:111], v[72:75], v[228:231], 0
	v_mfma_f32_16x16x32_bf16 v[104:107], v[80:83], v[228:231], 0
	v_mfma_f32_16x16x32_bf16 v[92:95], v[72:75], v[236:239], 0
	v_mfma_f32_16x16x32_bf16 v[84:87], v[80:83], v[236:239], 0
	v_mfma_f32_16x16x32_bf16 v[140:143], v[76:79], v[214:217], v[140:143]
	v_mfma_f32_16x16x32_bf16 v[136:139], v[88:91], v[214:217], v[136:139]
	v_mfma_f32_16x16x32_bf16 v[124:127], v[76:79], v[224:227], v[124:127]
	v_mfma_f32_16x16x32_bf16 v[120:123], v[88:91], v[224:227], v[120:123]
	v_mfma_f32_16x16x32_bf16 v[108:111], v[76:79], v[232:235], v[108:111]
	v_mfma_f32_16x16x32_bf16 v[104:107], v[88:91], v[232:235], v[104:107]
	v_mfma_f32_16x16x32_bf16 v[92:95], v[76:79], v[240:243], v[92:95]
	v_mfma_f32_16x16x32_bf16 v[84:87], v[88:91], v[240:243], v[84:87]
	s_setprio 0
	s_setprio 1
	v_mfma_f32_16x16x32_bf16 v[132:135], v[174:177], v[210:213], 0
	v_mfma_f32_16x16x32_bf16 v[128:131], v[190:193], v[210:213], 0
	v_mfma_f32_16x16x32_bf16 v[116:119], v[174:177], v[218:221], 0
	v_mfma_f32_16x16x32_bf16 v[112:115], v[190:193], v[218:221], 0
	v_mfma_f32_16x16x32_bf16 v[100:103], v[174:177], v[228:231], 0
	v_mfma_f32_16x16x32_bf16 v[96:99], v[190:193], v[228:231], 0
	v_mfma_f32_16x16x32_bf16 v[68:71], v[174:177], v[236:239], 0
	v_mfma_f32_16x16x32_bf16 v[64:67], v[190:193], v[236:239], 0
	v_mfma_f32_16x16x32_bf16 v[132:135], v[178:181], v[214:217], v[132:135]
	v_mfma_f32_16x16x32_bf16 v[128:131], v[194:197], v[214:217], v[128:131]
	v_mfma_f32_16x16x32_bf16 v[116:119], v[178:181], v[224:227], v[116:119]
	v_mfma_f32_16x16x32_bf16 v[112:115], v[194:197], v[224:227], v[112:115]
	v_mfma_f32_16x16x32_bf16 v[100:103], v[178:181], v[232:235], v[100:103]
	v_mfma_f32_16x16x32_bf16 v[96:99], v[194:197], v[232:235], v[96:99]
	v_mfma_f32_16x16x32_bf16 v[68:71], v[178:181], v[240:243], v[68:71]
	v_mfma_f32_16x16x32_bf16 v[64:67], v[194:197], v[240:243], v[64:67]
	s_setprio 0
	s_barrier
	s_add_i32 s83, s83, s8
	v_lshl_add_u64 v[182:183], s[44:45], 0, v[152:153]
	s_mov_b32 m0, s83
	ds_read_b128 v[210:213], v188 offset:16384
	ds_read_b128 v[214:217], v188 offset:17408
	ds_read_b128 v[218:221], v188 offset:18432
	ds_read_b128 v[224:227], v188 offset:19456
	ds_read_b128 v[228:231], v188 offset:20480
	ds_read_b128 v[232:235], v188 offset:21504
	ds_read_b128 v[236:239], v188 offset:22528
	ds_read_b128 v[240:243], v188 offset:23552
	global_load_lds_dwordx4 v[182:183], off
	s_add_i32 m0, s83, 0x2000
	s_add_u32 s84, s44, 0x40000
	v_lshl_add_u64 v[198:199], s[44:45], 0, v[144:145]
	s_addc_u32 s85, s45, 0
	s_add_i32 s83, s86, s8
	global_load_lds_dwordx4 v[198:199], off
	v_lshl_add_u64 v[244:245], s[84:85], 0, v[152:153]
	s_mov_b32 m0, s83
	v_lshl_add_u64 v[246:247], s[62:63], 0, v[146:147]
	global_load_lds_dwordx4 v[244:245], off
	v_lshl_add_u64 v[244:245], s[84:85], 0, v[144:145]
	s_add_i32 m0, s83, 0x2000
	s_nop 0
	global_load_lds_dwordx4 v[244:245], off
	v_lshl_add_u64 v[244:245], s[62:63], 0, v[148:149]
	s_mov_b32 m0, s59
	s_nop 0
	global_load_lds_dwordx4 v[244:245], off
	s_mov_b32 m0, s66
	s_nop 0
	global_load_lds_dwordx4 v[246:247], off
	s_waitcnt vmcnt(8)
	s_waitcnt lgkmcnt(0)
	s_barrier
	s_setprio 1
	s_waitcnt lgkmcnt(0)
	v_mfma_f32_16x16x32_bf16 v[60:63], v[72:75], v[210:213], 0
	v_mfma_f32_16x16x32_bf16 v[56:59], v[80:83], v[210:213], 0
	v_mfma_f32_16x16x32_bf16 v[44:47], v[72:75], v[218:221], 0
	v_mfma_f32_16x16x32_bf16 v[40:43], v[80:83], v[218:221], 0
	v_mfma_f32_16x16x32_bf16 v[28:31], v[72:75], v[228:231], 0
	v_mfma_f32_16x16x32_bf16 v[24:27], v[80:83], v[228:231], 0
	v_mfma_f32_16x16x32_bf16 v[12:15], v[72:75], v[236:239], 0
	v_mfma_f32_16x16x32_bf16 v[8:11], v[80:83], v[236:239], 0
	v_mfma_f32_16x16x32_bf16 v[60:63], v[76:79], v[214:217], v[60:63]
	v_mfma_f32_16x16x32_bf16 v[56:59], v[88:91], v[214:217], v[56:59]
	v_mfma_f32_16x16x32_bf16 v[44:47], v[76:79], v[224:227], v[44:47]
	v_mfma_f32_16x16x32_bf16 v[40:43], v[88:91], v[224:227], v[40:43]
	v_mfma_f32_16x16x32_bf16 v[28:31], v[76:79], v[232:235], v[28:31]
	v_mfma_f32_16x16x32_bf16 v[24:27], v[88:91], v[232:235], v[24:27]
	v_mfma_f32_16x16x32_bf16 v[12:15], v[76:79], v[240:243], v[12:15]
	v_mfma_f32_16x16x32_bf16 v[8:11], v[88:91], v[240:243], v[8:11]
	s_setprio 0
	s_setprio 1
	v_mfma_f32_16x16x32_bf16 v[52:55], v[174:177], v[210:213], 0
	v_mfma_f32_16x16x32_bf16 v[48:51], v[190:193], v[210:213], 0
	v_mfma_f32_16x16x32_bf16 v[36:39], v[174:177], v[218:221], 0
	v_mfma_f32_16x16x32_bf16 v[32:35], v[190:193], v[218:221], 0
	v_mfma_f32_16x16x32_bf16 v[20:23], v[174:177], v[228:231], 0
	v_mfma_f32_16x16x32_bf16 v[16:19], v[190:193], v[228:231], 0
	v_mfma_f32_16x16x32_bf16 v[4:7], v[174:177], v[236:239], 0
	v_mfma_f32_16x16x32_bf16 v[0:3], v[190:193], v[236:239], 0
	v_mfma_f32_16x16x32_bf16 v[52:55], v[178:181], v[214:217], v[52:55]
	v_mfma_f32_16x16x32_bf16 v[48:51], v[194:197], v[214:217], v[48:51]
	v_mfma_f32_16x16x32_bf16 v[36:39], v[178:181], v[224:227], v[36:39]
	v_mfma_f32_16x16x32_bf16 v[32:35], v[194:197], v[224:227], v[32:35]
	v_mfma_f32_16x16x32_bf16 v[20:23], v[178:181], v[232:235], v[20:23]
	v_mfma_f32_16x16x32_bf16 v[16:19], v[194:197], v[232:235], v[16:19]
	v_mfma_f32_16x16x32_bf16 v[4:7], v[178:181], v[240:243], v[4:7]
	v_mfma_f32_16x16x32_bf16 v[0:3], v[194:197], v[240:243], v[0:3]
	s_setprio 0
	s_barrier
	s_add_i32 s83, 0, 0x18000
	s_add_i32 s84, 0, 0x1c000
	v_add_u32_e32 v88, s83, v185
	v_add_u32_e32 v189, s84, v185
	ds_read_b128 v[72:75], v88
	ds_read_b128 v[76:79], v88 offset:1024
	ds_read_b128 v[80:83], v88 offset:2048
	ds_read_b128 v[88:91], v88 offset:3072
	ds_read_b128 v[174:177], v189
	ds_read_b128 v[178:181], v189 offset:1024
	ds_read_b128 v[190:193], v189 offset:2048
	ds_read_b128 v[194:197], v189 offset:3072
	s_add_u32 s62, s62, 0x40000
	s_addc_u32 s63, s63, 0
	s_mov_b32 m0, s67
	v_lshl_add_u64 v[248:249], s[62:63], 0, v[148:149]
	ds_read_b128 v[210:213], v188 offset:32768
	ds_read_b128 v[214:217], v188 offset:33792
	ds_read_b128 v[218:221], v188 offset:34816
	ds_read_b128 v[224:227], v188 offset:35840
	ds_read_b128 v[228:231], v188 offset:36864
	ds_read_b128 v[232:235], v188 offset:37888
	ds_read_b128 v[236:239], v188 offset:38912
	ds_read_b128 v[240:243], v188 offset:39936
	global_load_lds_dwordx4 v[248:249], off
	v_lshl_add_u64 v[248:249], s[62:63], 0, v[146:147]
	s_mov_b32 m0, s68
	s_nop 0
	global_load_lds_dwordx4 v[248:249], off
	s_waitcnt vmcnt(8)
	s_waitcnt lgkmcnt(0)
	s_barrier
	s_setprio 1
	s_waitcnt lgkmcnt(0)
	v_mfma_f32_16x16x32_bf16 v[140:143], v[72:75], v[210:213], v[140:143]
	v_mfma_f32_16x16x32_bf16 v[136:139], v[80:83], v[210:213], v[136:139]
	v_mfma_f32_16x16x32_bf16 v[124:127], v[72:75], v[218:221], v[124:127]
	v_mfma_f32_16x16x32_bf16 v[120:123], v[80:83], v[218:221], v[120:123]
	v_mfma_f32_16x16x32_bf16 v[108:111], v[72:75], v[228:231], v[108:111]
	v_mfma_f32_16x16x32_bf16 v[104:107], v[80:83], v[228:231], v[104:107]
	v_mfma_f32_16x16x32_bf16 v[92:95], v[72:75], v[236:239], v[92:95]
	v_mfma_f32_16x16x32_bf16 v[84:87], v[80:83], v[236:239], v[84:87]
	v_mfma_f32_16x16x32_bf16 v[140:143], v[76:79], v[214:217], v[140:143]
	v_mfma_f32_16x16x32_bf16 v[136:139], v[88:91], v[214:217], v[136:139]
	v_mfma_f32_16x16x32_bf16 v[124:127], v[76:79], v[224:227], v[124:127]
	v_mfma_f32_16x16x32_bf16 v[120:123], v[88:91], v[224:227], v[120:123]
	v_mfma_f32_16x16x32_bf16 v[108:111], v[76:79], v[232:235], v[108:111]
	v_mfma_f32_16x16x32_bf16 v[104:107], v[88:91], v[232:235], v[104:107]
	v_mfma_f32_16x16x32_bf16 v[92:95], v[76:79], v[240:243], v[92:95]
	v_mfma_f32_16x16x32_bf16 v[84:87], v[88:91], v[240:243], v[84:87]
	s_setprio 0
	s_setprio 1
	v_mfma_f32_16x16x32_bf16 v[132:135], v[174:177], v[210:213], v[132:135]
	v_mfma_f32_16x16x32_bf16 v[128:131], v[190:193], v[210:213], v[128:131]
	v_mfma_f32_16x16x32_bf16 v[116:119], v[174:177], v[218:221], v[116:119]
	v_mfma_f32_16x16x32_bf16 v[112:115], v[190:193], v[218:221], v[112:115]
	v_mfma_f32_16x16x32_bf16 v[100:103], v[174:177], v[228:231], v[100:103]
	v_mfma_f32_16x16x32_bf16 v[96:99], v[190:193], v[228:231], v[96:99]
	v_mfma_f32_16x16x32_bf16 v[68:71], v[174:177], v[236:239], v[68:71]
	v_mfma_f32_16x16x32_bf16 v[64:67], v[190:193], v[236:239], v[64:67]
	v_mfma_f32_16x16x32_bf16 v[132:135], v[178:181], v[214:217], v[132:135]
	v_mfma_f32_16x16x32_bf16 v[128:131], v[194:197], v[214:217], v[128:131]
	v_mfma_f32_16x16x32_bf16 v[116:119], v[178:181], v[224:227], v[116:119]
	v_mfma_f32_16x16x32_bf16 v[112:115], v[194:197], v[224:227], v[112:115]
	v_mfma_f32_16x16x32_bf16 v[100:103], v[178:181], v[232:235], v[100:103]
	v_mfma_f32_16x16x32_bf16 v[96:99], v[194:197], v[232:235], v[96:99]
	v_mfma_f32_16x16x32_bf16 v[68:71], v[178:181], v[240:243], v[68:71]
	v_mfma_f32_16x16x32_bf16 v[64:67], v[194:197], v[240:243], v[64:67]
	s_setprio 0
	s_barrier
	s_add_i32 s62, s83, s8
	v_lshl_add_u64 v[182:183], v[182:183], 0, s[22:23]
	s_mov_b32 m0, s62
	ds_read_b128 v[210:213], v188 offset:49152
	ds_read_b128 v[214:217], v188 offset:50176
	ds_read_b128 v[218:221], v188 offset:51200
	ds_read_b128 v[224:227], v188 offset:52224
	ds_read_b128 v[228:231], v188 offset:53248
	ds_read_b128 v[232:235], v188 offset:54272
	ds_read_b128 v[236:239], v188 offset:55296
	ds_read_b128 v[240:243], v188 offset:56320
	global_load_lds_dwordx4 v[182:183], off
	s_add_i32 m0, s62, 0x2000
	s_add_u32 s44, s44, 0x40080
	v_lshl_add_u64 v[182:183], v[198:199], 0, s[22:23]
	s_addc_u32 s45, s45, 0
	s_add_i32 s62, s84, s8
	global_load_lds_dwordx4 v[182:183], off
	v_lshl_add_u64 v[182:183], s[44:45], 0, v[152:153]
	s_mov_b32 m0, s62
	s_nop 0
	global_load_lds_dwordx4 v[182:183], off
	v_lshl_add_u64 v[182:183], s[44:45], 0, v[144:145]
	s_add_i32 m0, s62, 0x2000
	s_nop 0
	global_load_lds_dwordx4 v[182:183], off
	v_lshl_add_u64 v[182:183], v[244:245], 0, s[22:23]
	s_mov_b32 m0, s69
	s_nop 0
	global_load_lds_dwordx4 v[182:183], off
	v_lshl_add_u64 v[182:183], v[246:247], 0, s[22:23]
	s_mov_b32 m0, s74
	s_nop 0
	global_load_lds_dwordx4 v[182:183], off
	s_waitcnt vmcnt(8)
	s_waitcnt lgkmcnt(0)
	s_barrier
	s_setprio 1
	s_waitcnt lgkmcnt(0)
	v_mfma_f32_16x16x32_bf16 v[60:63], v[72:75], v[210:213], v[60:63]
	v_mfma_f32_16x16x32_bf16 v[56:59], v[80:83], v[210:213], v[56:59]
	v_mfma_f32_16x16x32_bf16 v[44:47], v[72:75], v[218:221], v[44:47]
	v_mfma_f32_16x16x32_bf16 v[40:43], v[80:83], v[218:221], v[40:43]
	v_mfma_f32_16x16x32_bf16 v[28:31], v[72:75], v[228:231], v[28:31]
	v_mfma_f32_16x16x32_bf16 v[24:27], v[80:83], v[228:231], v[24:27]
	v_mfma_f32_16x16x32_bf16 v[12:15], v[72:75], v[236:239], v[12:15]
	v_mfma_f32_16x16x32_bf16 v[8:11], v[80:83], v[236:239], v[8:11]
	v_mfma_f32_16x16x32_bf16 v[60:63], v[76:79], v[214:217], v[60:63]
	v_mfma_f32_16x16x32_bf16 v[56:59], v[88:91], v[214:217], v[56:59]
	v_mfma_f32_16x16x32_bf16 v[44:47], v[76:79], v[224:227], v[44:47]
	v_mfma_f32_16x16x32_bf16 v[40:43], v[88:91], v[224:227], v[40:43]
	v_mfma_f32_16x16x32_bf16 v[28:31], v[76:79], v[232:235], v[28:31]
	v_mfma_f32_16x16x32_bf16 v[24:27], v[88:91], v[232:235], v[24:27]
	v_mfma_f32_16x16x32_bf16 v[12:15], v[76:79], v[240:243], v[12:15]
	v_mfma_f32_16x16x32_bf16 v[8:11], v[88:91], v[240:243], v[8:11]
	s_setprio 0
	s_setprio 1
	v_mfma_f32_16x16x32_bf16 v[52:55], v[174:177], v[210:213], v[52:55]
	v_mfma_f32_16x16x32_bf16 v[48:51], v[190:193], v[210:213], v[48:51]
	v_mfma_f32_16x16x32_bf16 v[36:39], v[174:177], v[218:221], v[36:39]
	v_mfma_f32_16x16x32_bf16 v[32:35], v[190:193], v[218:221], v[32:35]
	v_mfma_f32_16x16x32_bf16 v[20:23], v[174:177], v[228:231], v[20:23]
	v_mfma_f32_16x16x32_bf16 v[16:19], v[190:193], v[228:231], v[16:19]
	v_mfma_f32_16x16x32_bf16 v[4:7], v[174:177], v[236:239], v[4:7]
	v_mfma_f32_16x16x32_bf16 v[0:3], v[190:193], v[236:239], v[0:3]
	v_mfma_f32_16x16x32_bf16 v[52:55], v[178:181], v[214:217], v[52:55]
	v_mfma_f32_16x16x32_bf16 v[48:51], v[194:197], v[214:217], v[48:51]
	v_mfma_f32_16x16x32_bf16 v[36:39], v[178:181], v[224:227], v[36:39]
	v_mfma_f32_16x16x32_bf16 v[32:35], v[194:197], v[224:227], v[32:35]
	v_mfma_f32_16x16x32_bf16 v[20:23], v[178:181], v[232:235], v[20:23]
	v_mfma_f32_16x16x32_bf16 v[16:19], v[194:197], v[232:235], v[16:19]
	v_mfma_f32_16x16x32_bf16 v[4:7], v[178:181], v[240:243], v[4:7]
	v_mfma_f32_16x16x32_bf16 v[0:3], v[194:197], v[240:243], v[0:3]
	s_setprio 0
	s_barrier
	s_add_i32 s82, s82, 2
	s_add_u32 s80, s80, 0x100
	s_addc_u32 s81, s81, 0
	s_add_u32 s48, s48, 0x100
	s_addc_u32 s49, s49, 0
	s_cmp_gt_u32 s82, 13
	.p2align	6

.LBB0_704:
	s_ashr_i32 s21, s20, 31
	s_lshl_b64 s[48:49], s[20:21], 18
	v_readlane_b32 s19, v254, 14
	s_add_u32 s48, s19, s48
	v_readlane_b32 s19, v254, 15
	s_addc_u32 s49, s19, s49
	s_and_b64 s[50:51], s[46:47], exec
	s_cselect_b32 s21, s49, s45
	s_cselect_b32 s78, s48, s44
	s_ashr_i32 s19, s18, 31
	s_lshl_b64 s[50:51], s[18:19], 18
	v_readlane_b32 s19, v254, 10
	s_add_u32 s50, s19, s50
	v_readlane_b32 s19, v254, 11
	s_addc_u32 s51, s19, s51
	s_and_b64 s[62:63], s[46:47], exec
	s_cselect_b32 s19, s51, s61
	s_cselect_b32 s79, s50, s60
	s_add_u32 s80, s60, 0x100
	s_addc_u32 s81, s61, 0
	s_add_u32 s60, s44, 0x20080
	s_addc_u32 s61, s45, 0
	s_mov_b32 s82, -2
	s_add_u32 s44, s60, 0xfffe0080
	s_addc_u32 s45, s61, -1
	s_cmp_eq_u32 s82, 4
	s_cselect_b32 s63, s21, s45
	s_cselect_b32 s62, s78, s44
	s_cselect_b32 s45, s19, s81
	s_cselect_b32 s44, s79, s80
	v_lshl_add_u64 v[198:199], s[60:61], 0, v[180:181]
	s_add_i32 m0, s59, 0xc000
	global_load_lds_dwordx4 v[198:199], off
	v_lshl_add_u64 v[198:199], s[60:61], 0, v[178:179]
	s_add_i32 m0, s59, 0xe000
	s_nop 0
	global_load_lds_dwordx4 v[198:199], off
	s_waitcnt vmcnt(8)
	s_waitcnt lgkmcnt(0)
	s_barrier
	s_setprio 1
	s_waitcnt lgkmcnt(0)
	v_mfma_f32_16x16x32_bf16 v[128:131], v[124:127], v[190:193], 0
	v_mfma_f32_16x16x32_bf16 v[120:123], v[136:139], v[190:193], 0
	v_mfma_f32_16x16x32_bf16 v[108:111], v[124:127], v[214:217], 0
	v_mfma_f32_16x16x32_bf16 v[104:107], v[136:139], v[214:217], 0
	v_mfma_f32_16x16x32_bf16 v[92:95], v[124:127], v[224:227], 0
	v_mfma_f32_16x16x32_bf16 v[88:91], v[136:139], v[224:227], 0
	v_mfma_f32_16x16x32_bf16 v[76:79], v[124:127], v[232:235], 0
	v_mfma_f32_16x16x32_bf16 v[72:75], v[136:139], v[232:235], 0
	v_mfma_f32_16x16x32_bf16 v[128:131], v[132:135], v[210:213], v[128:131]
	v_mfma_f32_16x16x32_bf16 v[120:123], v[140:143], v[210:213], v[120:123]
	v_mfma_f32_16x16x32_bf16 v[108:111], v[132:135], v[218:221], v[108:111]
	v_mfma_f32_16x16x32_bf16 v[104:107], v[140:143], v[218:221], v[104:107]
	v_mfma_f32_16x16x32_bf16 v[92:95], v[132:135], v[228:231], v[92:95]
	v_mfma_f32_16x16x32_bf16 v[88:91], v[140:143], v[228:231], v[88:91]
	v_mfma_f32_16x16x32_bf16 v[76:79], v[132:135], v[236:239], v[76:79]
	v_mfma_f32_16x16x32_bf16 v[72:75], v[140:143], v[236:239], v[72:75]
	s_setprio 0
	s_setprio 1
	v_mfma_f32_16x16x32_bf16 v[116:119], v[144:147], v[190:193], 0
	v_mfma_f32_16x16x32_bf16 v[112:115], v[182:185], v[190:193], 0
	v_mfma_f32_16x16x32_bf16 v[100:103], v[144:147], v[214:217], 0
	v_mfma_f32_16x16x32_bf16 v[96:99], v[182:185], v[214:217], 0
	v_mfma_f32_16x16x32_bf16 v[84:87], v[144:147], v[224:227], 0
	v_mfma_f32_16x16x32_bf16 v[80:83], v[182:185], v[224:227], 0
	v_mfma_f32_16x16x32_bf16 v[68:71], v[144:147], v[232:235], 0
	v_mfma_f32_16x16x32_bf16 v[64:67], v[182:185], v[232:235], 0
	v_mfma_f32_16x16x32_bf16 v[116:119], v[148:151], v[210:213], v[116:119]
	v_mfma_f32_16x16x32_bf16 v[112:115], v[186:189], v[210:213], v[112:115]
	v_mfma_f32_16x16x32_bf16 v[100:103], v[148:151], v[218:221], v[100:103]
	v_mfma_f32_16x16x32_bf16 v[96:99], v[186:189], v[218:221], v[96:99]
	v_mfma_f32_16x16x32_bf16 v[84:87], v[148:151], v[228:231], v[84:87]
	v_mfma_f32_16x16x32_bf16 v[80:83], v[186:189], v[228:231], v[80:83]
	v_mfma_f32_16x16x32_bf16 v[68:71], v[148:151], v[236:239], v[68:71]
	v_mfma_f32_16x16x32_bf16 v[64:67], v[186:189], v[236:239], v[64:67]
	s_setprio 0
	s_barrier
	s_add_i32 s83, s83, s8
	v_lshl_add_u64 v[198:199], s[44:45], 0, v[152:153]
	s_mov_b32 m0, s83
	ds_read_b128 v[190:193], v197 offset:16384
	ds_read_b128 v[210:213], v197 offset:17408
	ds_read_b128 v[214:217], v197 offset:18432
	ds_read_b128 v[218:221], v197 offset:19456
	ds_read_b128 v[224:227], v197 offset:20480
	ds_read_b128 v[228:231], v197 offset:21504
	ds_read_b128 v[232:235], v197 offset:22528
	ds_read_b128 v[236:239], v197 offset:23552
	global_load_lds_dwordx4 v[198:199], off
	s_add_i32 m0, s83, 0x2000
	s_add_u32 s84, s44, 0x20000
	v_lshl_add_u64 v[240:241], s[44:45], 0, v[172:173]
	s_addc_u32 s85, s45, 0
	s_add_i32 s83, s86, s8
	global_load_lds_dwordx4 v[240:241], off
	v_lshl_add_u64 v[242:243], s[84:85], 0, v[152:153]
	s_mov_b32 m0, s83
	v_lshl_add_u64 v[244:245], s[62:63], 0, v[174:175]
	global_load_lds_dwordx4 v[242:243], off
	v_lshl_add_u64 v[242:243], s[84:85], 0, v[172:173]
	s_add_i32 m0, s83, 0x2000
	s_nop 0
	global_load_lds_dwordx4 v[242:243], off
	v_lshl_add_u64 v[242:243], s[62:63], 0, v[176:177]
	s_mov_b32 m0, s59
	s_nop 0
	global_load_lds_dwordx4 v[242:243], off
	s_mov_b32 m0, s66
	s_nop 0
	global_load_lds_dwordx4 v[244:245], off
	s_waitcnt vmcnt(8)
	s_waitcnt lgkmcnt(0)
	s_barrier
	s_setprio 1
	s_waitcnt lgkmcnt(0)
	v_mfma_f32_16x16x32_bf16 v[60:63], v[124:127], v[190:193], 0
	v_mfma_f32_16x16x32_bf16 v[56:59], v[136:139], v[190:193], 0
	v_mfma_f32_16x16x32_bf16 v[48:51], v[124:127], v[214:217], 0
	v_mfma_f32_16x16x32_bf16 v[40:43], v[136:139], v[214:217], 0
	v_mfma_f32_16x16x32_bf16 v[32:35], v[124:127], v[224:227], 0
	v_mfma_f32_16x16x32_bf16 v[24:27], v[136:139], v[224:227], 0
	v_mfma_f32_16x16x32_bf16 v[16:19], v[124:127], v[232:235], 0
	v_mfma_f32_16x16x32_bf16 v[8:11], v[136:139], v[232:235], 0
	v_mfma_f32_16x16x32_bf16 v[60:63], v[132:135], v[210:213], v[60:63]
	v_mfma_f32_16x16x32_bf16 v[56:59], v[140:143], v[210:213], v[56:59]
	v_mfma_f32_16x16x32_bf16 v[48:51], v[132:135], v[218:221], v[48:51]
	v_mfma_f32_16x16x32_bf16 v[40:43], v[140:143], v[218:221], v[40:43]
	v_mfma_f32_16x16x32_bf16 v[32:35], v[132:135], v[228:231], v[32:35]
	v_mfma_f32_16x16x32_bf16 v[24:27], v[140:143], v[228:231], v[24:27]
	v_mfma_f32_16x16x32_bf16 v[16:19], v[132:135], v[236:239], v[16:19]
	v_mfma_f32_16x16x32_bf16 v[8:11], v[140:143], v[236:239], v[8:11]
	s_setprio 0
	s_setprio 1
	v_mfma_f32_16x16x32_bf16 v[52:55], v[144:147], v[190:193], 0
	v_mfma_f32_16x16x32_bf16 v[44:47], v[182:185], v[190:193], 0
	v_mfma_f32_16x16x32_bf16 v[36:39], v[144:147], v[214:217], 0
	v_mfma_f32_16x16x32_bf16 v[28:31], v[182:185], v[214:217], 0
	v_mfma_f32_16x16x32_bf16 v[20:23], v[144:147], v[224:227], 0
	v_mfma_f32_16x16x32_bf16 v[12:15], v[182:185], v[224:227], 0
	v_mfma_f32_16x16x32_bf16 v[4:7], v[144:147], v[232:235], 0
	v_mfma_f32_16x16x32_bf16 v[0:3], v[182:185], v[232:235], 0
	v_mfma_f32_16x16x32_bf16 v[52:55], v[148:151], v[210:213], v[52:55]
	v_mfma_f32_16x16x32_bf16 v[44:47], v[186:189], v[210:213], v[44:47]
	v_mfma_f32_16x16x32_bf16 v[36:39], v[148:151], v[218:221], v[36:39]
	v_mfma_f32_16x16x32_bf16 v[28:31], v[186:189], v[218:221], v[28:31]
	v_mfma_f32_16x16x32_bf16 v[20:23], v[148:151], v[228:231], v[20:23]
	v_mfma_f32_16x16x32_bf16 v[12:15], v[186:189], v[228:231], v[12:15]
	v_mfma_f32_16x16x32_bf16 v[4:7], v[148:151], v[236:239], v[4:7]
	v_mfma_f32_16x16x32_bf16 v[0:3], v[186:189], v[236:239], v[0:3]
	s_setprio 0
	s_barrier
	s_add_i32 s83, 0, 0x18000
	s_add_i32 s84, 0, 0x1c000
	v_add_u32_e32 v140, s83, v195
	v_add_u32_e32 v186, s84, v195
	ds_read_b128 v[124:127], v140
	ds_read_b128 v[132:135], v140 offset:1024
	ds_read_b128 v[136:139], v140 offset:2048
	ds_read_b128 v[140:143], v140 offset:3072
	ds_read_b128 v[144:147], v186
	ds_read_b128 v[148:151], v186 offset:1024
	ds_read_b128 v[182:185], v186 offset:2048
	ds_read_b128 v[186:189], v186 offset:3072
	s_add_u32 s62, s62, 0x20000
	s_addc_u32 s63, s63, 0
	s_mov_b32 m0, s67
	v_lshl_add_u64 v[246:247], s[62:63], 0, v[176:177]
	ds_read_b128 v[190:193], v197 offset:32768
	ds_read_b128 v[210:213], v197 offset:33792
	ds_read_b128 v[214:217], v197 offset:34816
	ds_read_b128 v[218:221], v197 offset:35840
	ds_read_b128 v[224:227], v197 offset:36864
	ds_read_b128 v[228:231], v197 offset:37888
	ds_read_b128 v[232:235], v197 offset:38912
	ds_read_b128 v[236:239], v197 offset:39936
	global_load_lds_dwordx4 v[246:247], off
	v_lshl_add_u64 v[246:247], s[62:63], 0, v[174:175]
	s_mov_b32 m0, s68
	s_nop 0
	global_load_lds_dwordx4 v[246:247], off
	s_waitcnt vmcnt(8)
	s_waitcnt lgkmcnt(0)
	s_barrier
	s_setprio 1
	s_waitcnt lgkmcnt(0)
	v_mfma_f32_16x16x32_bf16 v[128:131], v[124:127], v[190:193], v[128:131]
	v_mfma_f32_16x16x32_bf16 v[120:123], v[136:139], v[190:193], v[120:123]
	v_mfma_f32_16x16x32_bf16 v[108:111], v[124:127], v[214:217], v[108:111]
	v_mfma_f32_16x16x32_bf16 v[104:107], v[136:139], v[214:217], v[104:107]
	v_mfma_f32_16x16x32_bf16 v[92:95], v[124:127], v[224:227], v[92:95]
	v_mfma_f32_16x16x32_bf16 v[88:91], v[136:139], v[224:227], v[88:91]
	v_mfma_f32_16x16x32_bf16 v[76:79], v[124:127], v[232:235], v[76:79]
	v_mfma_f32_16x16x32_bf16 v[72:75], v[136:139], v[232:235], v[72:75]
	v_mfma_f32_16x16x32_bf16 v[128:131], v[132:135], v[210:213], v[128:131]
	v_mfma_f32_16x16x32_bf16 v[120:123], v[140:143], v[210:213], v[120:123]
	v_mfma_f32_16x16x32_bf16 v[108:111], v[132:135], v[218:221], v[108:111]
	v_mfma_f32_16x16x32_bf16 v[104:107], v[140:143], v[218:221], v[104:107]
	v_mfma_f32_16x16x32_bf16 v[92:95], v[132:135], v[228:231], v[92:95]
	v_mfma_f32_16x16x32_bf16 v[88:91], v[140:143], v[228:231], v[88:91]
	v_mfma_f32_16x16x32_bf16 v[76:79], v[132:135], v[236:239], v[76:79]
	v_mfma_f32_16x16x32_bf16 v[72:75], v[140:143], v[236:239], v[72:75]
	s_setprio 0
	s_setprio 1
	v_mfma_f32_16x16x32_bf16 v[116:119], v[144:147], v[190:193], v[116:119]
	v_mfma_f32_16x16x32_bf16 v[112:115], v[182:185], v[190:193], v[112:115]
	v_mfma_f32_16x16x32_bf16 v[100:103], v[144:147], v[214:217], v[100:103]
	v_mfma_f32_16x16x32_bf16 v[96:99], v[182:185], v[214:217], v[96:99]
	v_mfma_f32_16x16x32_bf16 v[84:87], v[144:147], v[224:227], v[84:87]
	v_mfma_f32_16x16x32_bf16 v[80:83], v[182:185], v[224:227], v[80:83]
	v_mfma_f32_16x16x32_bf16 v[68:71], v[144:147], v[232:235], v[68:71]
	v_mfma_f32_16x16x32_bf16 v[64:67], v[182:185], v[232:235], v[64:67]
	v_mfma_f32_16x16x32_bf16 v[116:119], v[148:151], v[210:213], v[116:119]
	v_mfma_f32_16x16x32_bf16 v[112:115], v[186:189], v[210:213], v[112:115]
	v_mfma_f32_16x16x32_bf16 v[100:103], v[148:151], v[218:221], v[100:103]
	v_mfma_f32_16x16x32_bf16 v[96:99], v[186:189], v[218:221], v[96:99]
	v_mfma_f32_16x16x32_bf16 v[84:87], v[148:151], v[228:231], v[84:87]
	v_mfma_f32_16x16x32_bf16 v[80:83], v[186:189], v[228:231], v[80:83]
	v_mfma_f32_16x16x32_bf16 v[68:71], v[148:151], v[236:239], v[68:71]
	v_mfma_f32_16x16x32_bf16 v[64:67], v[186:189], v[236:239], v[64:67]
	s_setprio 0
	s_barrier
	s_add_i32 s62, s83, s8
	v_lshl_add_u64 v[198:199], v[198:199], 0, s[22:23]
	s_mov_b32 m0, s62
	ds_read_b128 v[190:193], v197 offset:49152
	ds_read_b128 v[210:213], v197 offset:50176
	ds_read_b128 v[214:217], v197 offset:51200
	ds_read_b128 v[218:221], v197 offset:52224
	ds_read_b128 v[224:227], v197 offset:53248
	ds_read_b128 v[228:231], v197 offset:54272
	ds_read_b128 v[232:235], v197 offset:55296
	ds_read_b128 v[236:239], v197 offset:56320
	global_load_lds_dwordx4 v[198:199], off
	s_add_i32 m0, s62, 0x2000
	s_add_u32 s44, s44, 0x20080
	v_lshl_add_u64 v[198:199], v[240:241], 0, s[22:23]
	s_addc_u32 s45, s45, 0
	s_add_i32 s62, s84, s8
	global_load_lds_dwordx4 v[198:199], off
	v_lshl_add_u64 v[198:199], s[44:45], 0, v[152:153]
	s_mov_b32 m0, s62
	s_nop 0
	global_load_lds_dwordx4 v[198:199], off
	v_lshl_add_u64 v[198:199], s[44:45], 0, v[172:173]
	s_add_i32 m0, s62, 0x2000
	s_nop 0
	global_load_lds_dwordx4 v[198:199], off
	v_lshl_add_u64 v[198:199], v[242:243], 0, s[22:23]
	s_mov_b32 m0, s69
	s_nop 0
	global_load_lds_dwordx4 v[198:199], off
	v_lshl_add_u64 v[198:199], v[244:245], 0, s[22:23]
	s_mov_b32 m0, s74
	s_nop 0
	global_load_lds_dwordx4 v[198:199], off
	s_waitcnt vmcnt(8)
	s_waitcnt lgkmcnt(0)
	s_barrier
	s_setprio 1
	s_waitcnt lgkmcnt(0)
	v_mfma_f32_16x16x32_bf16 v[60:63], v[124:127], v[190:193], v[60:63]
	v_mfma_f32_16x16x32_bf16 v[56:59], v[136:139], v[190:193], v[56:59]
	v_mfma_f32_16x16x32_bf16 v[48:51], v[124:127], v[214:217], v[48:51]
	v_mfma_f32_16x16x32_bf16 v[40:43], v[136:139], v[214:217], v[40:43]
	v_mfma_f32_16x16x32_bf16 v[32:35], v[124:127], v[224:227], v[32:35]
	v_mfma_f32_16x16x32_bf16 v[24:27], v[136:139], v[224:227], v[24:27]
	v_mfma_f32_16x16x32_bf16 v[16:19], v[124:127], v[232:235], v[16:19]
	v_mfma_f32_16x16x32_bf16 v[8:11], v[136:139], v[232:235], v[8:11]
	v_mfma_f32_16x16x32_bf16 v[60:63], v[132:135], v[210:213], v[60:63]
	v_mfma_f32_16x16x32_bf16 v[56:59], v[140:143], v[210:213], v[56:59]
	v_mfma_f32_16x16x32_bf16 v[48:51], v[132:135], v[218:221], v[48:51]
	v_mfma_f32_16x16x32_bf16 v[40:43], v[140:143], v[218:221], v[40:43]
	v_mfma_f32_16x16x32_bf16 v[32:35], v[132:135], v[228:231], v[32:35]
	v_mfma_f32_16x16x32_bf16 v[24:27], v[140:143], v[228:231], v[24:27]
	v_mfma_f32_16x16x32_bf16 v[16:19], v[132:135], v[236:239], v[16:19]
	v_mfma_f32_16x16x32_bf16 v[8:11], v[140:143], v[236:239], v[8:11]
	s_setprio 0
	s_setprio 1
	v_mfma_f32_16x16x32_bf16 v[52:55], v[144:147], v[190:193], v[52:55]
	v_mfma_f32_16x16x32_bf16 v[44:47], v[182:185], v[190:193], v[44:47]
	v_mfma_f32_16x16x32_bf16 v[36:39], v[144:147], v[214:217], v[36:39]
	v_mfma_f32_16x16x32_bf16 v[28:31], v[182:185], v[214:217], v[28:31]
	v_mfma_f32_16x16x32_bf16 v[20:23], v[144:147], v[224:227], v[20:23]
	v_mfma_f32_16x16x32_bf16 v[12:15], v[182:185], v[224:227], v[12:15]
	v_mfma_f32_16x16x32_bf16 v[4:7], v[144:147], v[232:235], v[4:7]
	v_mfma_f32_16x16x32_bf16 v[0:3], v[182:185], v[232:235], v[0:3]
	v_mfma_f32_16x16x32_bf16 v[52:55], v[148:151], v[210:213], v[52:55]
	v_mfma_f32_16x16x32_bf16 v[44:47], v[186:189], v[210:213], v[44:47]
	v_mfma_f32_16x16x32_bf16 v[36:39], v[148:151], v[218:221], v[36:39]
	v_mfma_f32_16x16x32_bf16 v[28:31], v[186:189], v[218:221], v[28:31]
	v_mfma_f32_16x16x32_bf16 v[20:23], v[148:151], v[228:231], v[20:23]
	v_mfma_f32_16x16x32_bf16 v[12:15], v[186:189], v[228:231], v[12:15]
	v_mfma_f32_16x16x32_bf16 v[4:7], v[148:151], v[236:239], v[4:7]
	v_mfma_f32_16x16x32_bf16 v[0:3], v[186:189], v[236:239], v[0:3]
	s_setprio 0
	s_barrier
	s_add_i32 s82, s82, 2
	s_add_u32 s80, s80, 0x100
	s_addc_u32 s81, s81, 0
	s_add_u32 s60, s60, 0x100
	s_addc_u32 s61, s61, 0
	s_cmp_gt_u32 s82, 5
	.p2align	6

.LBB0_724:
	s_ashr_i32 s21, s20, 31
	s_lshl_b64 s[48:49], s[20:21], 18
	v_readlane_b32 s19, v254, 28
	s_add_u32 s48, s19, s48
	v_readlane_b32 s19, v254, 29
	s_addc_u32 s49, s19, s49
	s_and_b64 s[50:51], s[46:47], exec
	s_cselect_b32 s21, s49, s45
	s_cselect_b32 s78, s48, s44
	s_ashr_i32 s19, s18, 31
	s_lshl_b64 s[50:51], s[18:19], 18
	v_readlane_b32 s19, v254, 24
	s_add_u32 s50, s19, s50
	v_readlane_b32 s19, v254, 25
	s_addc_u32 s51, s19, s51
	s_and_b64 s[62:63], s[46:47], exec
	s_cselect_b32 s19, s51, s61
	s_cselect_b32 s79, s50, s60
	s_add_u32 s80, s60, 0x100
	s_addc_u32 s81, s61, 0
	s_add_u32 s60, s44, 0x20080
	s_addc_u32 s61, s45, 0
	s_mov_b32 s82, -2
	s_add_u32 s44, s60, 0xfffe0080
	s_addc_u32 s45, s61, -1
	s_cmp_eq_u32 s82, 4
	s_cselect_b32 s63, s21, s45
	s_cselect_b32 s62, s78, s44
	s_cselect_b32 s45, s19, s81
	s_cselect_b32 s44, s79, s80
	v_lshl_add_u64 v[178:179], s[60:61], 0, v[172:173]
	s_add_i32 m0, s59, 0xc000
	global_load_lds_dwordx4 v[178:179], off
	v_lshl_add_u64 v[178:179], s[60:61], 0, v[150:151]
	s_add_i32 m0, s59, 0xe000
	s_nop 0
	global_load_lds_dwordx4 v[178:179], off
	s_waitcnt vmcnt(8)
	s_waitcnt lgkmcnt(0)
	s_barrier
	s_setprio 1
	s_waitcnt lgkmcnt(0)
	v_mfma_f32_16x16x32_bf16 v[124:127], v[128:131], v[196:199], 0
	v_mfma_f32_16x16x32_bf16 v[120:123], v[136:139], v[196:199], 0
	v_mfma_f32_16x16x32_bf16 v[108:111], v[128:131], v[214:217], 0
	v_mfma_f32_16x16x32_bf16 v[104:107], v[136:139], v[214:217], 0
	v_mfma_f32_16x16x32_bf16 v[92:95], v[128:131], v[224:227], 0
	v_mfma_f32_16x16x32_bf16 v[88:91], v[136:139], v[224:227], 0
	v_mfma_f32_16x16x32_bf16 v[76:79], v[128:131], v[232:235], 0
	v_mfma_f32_16x16x32_bf16 v[72:75], v[136:139], v[232:235], 0
	v_mfma_f32_16x16x32_bf16 v[124:127], v[132:135], v[210:213], v[124:127]
	v_mfma_f32_16x16x32_bf16 v[120:123], v[140:143], v[210:213], v[120:123]
	v_mfma_f32_16x16x32_bf16 v[108:111], v[132:135], v[218:221], v[108:111]
	v_mfma_f32_16x16x32_bf16 v[104:107], v[140:143], v[218:221], v[104:107]
	v_mfma_f32_16x16x32_bf16 v[92:95], v[132:135], v[228:231], v[92:95]
	v_mfma_f32_16x16x32_bf16 v[88:91], v[140:143], v[228:231], v[88:91]
	v_mfma_f32_16x16x32_bf16 v[76:79], v[132:135], v[236:239], v[76:79]
	v_mfma_f32_16x16x32_bf16 v[72:75], v[140:143], v[236:239], v[72:75]
	s_setprio 0
	s_setprio 1
	v_mfma_f32_16x16x32_bf16 v[116:119], v[174:177], v[196:199], 0
	v_mfma_f32_16x16x32_bf16 v[112:115], v[188:191], v[196:199], 0
	v_mfma_f32_16x16x32_bf16 v[100:103], v[174:177], v[214:217], 0
	v_mfma_f32_16x16x32_bf16 v[96:99], v[188:191], v[214:217], 0
	v_mfma_f32_16x16x32_bf16 v[84:87], v[174:177], v[224:227], 0
	v_mfma_f32_16x16x32_bf16 v[80:83], v[188:191], v[224:227], 0
	v_mfma_f32_16x16x32_bf16 v[68:71], v[174:177], v[232:235], 0
	v_mfma_f32_16x16x32_bf16 v[64:67], v[188:191], v[232:235], 0
	v_mfma_f32_16x16x32_bf16 v[116:119], v[184:187], v[210:213], v[116:119]
	v_mfma_f32_16x16x32_bf16 v[112:115], v[192:195], v[210:213], v[112:115]
	v_mfma_f32_16x16x32_bf16 v[100:103], v[184:187], v[218:221], v[100:103]
	v_mfma_f32_16x16x32_bf16 v[96:99], v[192:195], v[218:221], v[96:99]
	v_mfma_f32_16x16x32_bf16 v[84:87], v[184:187], v[228:231], v[84:87]
	v_mfma_f32_16x16x32_bf16 v[80:83], v[192:195], v[228:231], v[80:83]
	v_mfma_f32_16x16x32_bf16 v[68:71], v[184:187], v[236:239], v[68:71]
	v_mfma_f32_16x16x32_bf16 v[64:67], v[192:195], v[236:239], v[64:67]
	s_setprio 0
	s_barrier
	s_add_i32 s83, s83, s8
	v_lshl_add_u64 v[178:179], s[44:45], 0, v[152:153]
	s_mov_b32 m0, s83
	ds_read_b128 v[196:199], v183 offset:16384
	ds_read_b128 v[210:213], v183 offset:17408
	ds_read_b128 v[214:217], v183 offset:18432
	ds_read_b128 v[218:221], v183 offset:19456
	ds_read_b128 v[224:227], v183 offset:20480
	ds_read_b128 v[228:231], v183 offset:21504
	ds_read_b128 v[232:235], v183 offset:22528
	ds_read_b128 v[236:239], v183 offset:23552
	global_load_lds_dwordx4 v[178:179], off
	s_add_i32 m0, s83, 0x2000
	s_add_u32 s84, s44, 0x20000
	v_lshl_add_u64 v[240:241], s[44:45], 0, v[144:145]
	s_addc_u32 s85, s45, 0
	s_add_i32 s83, s86, s8
	global_load_lds_dwordx4 v[240:241], off
	v_lshl_add_u64 v[242:243], s[84:85], 0, v[152:153]
	s_mov_b32 m0, s83
	v_lshl_add_u64 v[244:245], s[62:63], 0, v[146:147]
	global_load_lds_dwordx4 v[242:243], off
	v_lshl_add_u64 v[242:243], s[84:85], 0, v[144:145]
	s_add_i32 m0, s83, 0x2000
	s_nop 0
	global_load_lds_dwordx4 v[242:243], off
	v_lshl_add_u64 v[242:243], s[62:63], 0, v[148:149]
	s_mov_b32 m0, s59
	s_nop 0
	global_load_lds_dwordx4 v[242:243], off
	s_mov_b32 m0, s66
	s_nop 0
	global_load_lds_dwordx4 v[244:245], off
	s_waitcnt vmcnt(8)
	s_waitcnt lgkmcnt(0)
	s_barrier
	s_setprio 1
	s_waitcnt lgkmcnt(0)
	v_mfma_f32_16x16x32_bf16 v[60:63], v[128:131], v[196:199], 0
	v_mfma_f32_16x16x32_bf16 v[56:59], v[136:139], v[196:199], 0
	v_mfma_f32_16x16x32_bf16 v[44:47], v[128:131], v[214:217], 0
	v_mfma_f32_16x16x32_bf16 v[40:43], v[136:139], v[214:217], 0
	v_mfma_f32_16x16x32_bf16 v[28:31], v[128:131], v[224:227], 0
	v_mfma_f32_16x16x32_bf16 v[24:27], v[136:139], v[224:227], 0
	v_mfma_f32_16x16x32_bf16 v[12:15], v[128:131], v[232:235], 0
	v_mfma_f32_16x16x32_bf16 v[8:11], v[136:139], v[232:235], 0
	v_mfma_f32_16x16x32_bf16 v[60:63], v[132:135], v[210:213], v[60:63]
	v_mfma_f32_16x16x32_bf16 v[56:59], v[140:143], v[210:213], v[56:59]
	v_mfma_f32_16x16x32_bf16 v[44:47], v[132:135], v[218:221], v[44:47]
	v_mfma_f32_16x16x32_bf16 v[40:43], v[140:143], v[218:221], v[40:43]
	v_mfma_f32_16x16x32_bf16 v[28:31], v[132:135], v[228:231], v[28:31]
	v_mfma_f32_16x16x32_bf16 v[24:27], v[140:143], v[228:231], v[24:27]
	v_mfma_f32_16x16x32_bf16 v[12:15], v[132:135], v[236:239], v[12:15]
	v_mfma_f32_16x16x32_bf16 v[8:11], v[140:143], v[236:239], v[8:11]
	s_setprio 0
	s_setprio 1
	v_mfma_f32_16x16x32_bf16 v[52:55], v[174:177], v[196:199], 0
	v_mfma_f32_16x16x32_bf16 v[48:51], v[188:191], v[196:199], 0
	v_mfma_f32_16x16x32_bf16 v[36:39], v[174:177], v[214:217], 0
	v_mfma_f32_16x16x32_bf16 v[32:35], v[188:191], v[214:217], 0
	v_mfma_f32_16x16x32_bf16 v[20:23], v[174:177], v[224:227], 0
	v_mfma_f32_16x16x32_bf16 v[16:19], v[188:191], v[224:227], 0
	v_mfma_f32_16x16x32_bf16 v[4:7], v[174:177], v[232:235], 0
	v_mfma_f32_16x16x32_bf16 v[0:3], v[188:191], v[232:235], 0
	v_mfma_f32_16x16x32_bf16 v[52:55], v[184:187], v[210:213], v[52:55]
	v_mfma_f32_16x16x32_bf16 v[48:51], v[192:195], v[210:213], v[48:51]
	v_mfma_f32_16x16x32_bf16 v[36:39], v[184:187], v[218:221], v[36:39]
	v_mfma_f32_16x16x32_bf16 v[32:35], v[192:195], v[218:221], v[32:35]
	v_mfma_f32_16x16x32_bf16 v[20:23], v[184:187], v[228:231], v[20:23]
	v_mfma_f32_16x16x32_bf16 v[16:19], v[192:195], v[228:231], v[16:19]
	v_mfma_f32_16x16x32_bf16 v[4:7], v[184:187], v[236:239], v[4:7]
	v_mfma_f32_16x16x32_bf16 v[0:3], v[192:195], v[236:239], v[0:3]
	s_setprio 0
	s_barrier
	s_add_i32 s83, 0, 0x18000
	s_add_i32 s84, 0, 0x1c000
	v_add_u32_e32 v140, s83, v181
	v_add_u32_e32 v192, s84, v181
	ds_read_b128 v[128:131], v140
	ds_read_b128 v[132:135], v140 offset:1024
	ds_read_b128 v[136:139], v140 offset:2048
	ds_read_b128 v[140:143], v140 offset:3072
	ds_read_b128 v[174:177], v192
	ds_read_b128 v[184:187], v192 offset:1024
	ds_read_b128 v[188:191], v192 offset:2048
	ds_read_b128 v[192:195], v192 offset:3072
	s_add_u32 s62, s62, 0x20000
	s_addc_u32 s63, s63, 0
	s_mov_b32 m0, s67
	v_lshl_add_u64 v[246:247], s[62:63], 0, v[148:149]
	ds_read_b128 v[196:199], v183 offset:32768
	ds_read_b128 v[210:213], v183 offset:33792
	ds_read_b128 v[214:217], v183 offset:34816
	ds_read_b128 v[218:221], v183 offset:35840
	ds_read_b128 v[224:227], v183 offset:36864
	ds_read_b128 v[228:231], v183 offset:37888
	ds_read_b128 v[232:235], v183 offset:38912
	ds_read_b128 v[236:239], v183 offset:39936
	global_load_lds_dwordx4 v[246:247], off
	v_lshl_add_u64 v[246:247], s[62:63], 0, v[146:147]
	s_mov_b32 m0, s68
	s_nop 0
	global_load_lds_dwordx4 v[246:247], off
	s_waitcnt vmcnt(8)
	s_waitcnt lgkmcnt(0)
	s_barrier
	s_setprio 1
	s_waitcnt lgkmcnt(0)
	v_mfma_f32_16x16x32_bf16 v[124:127], v[128:131], v[196:199], v[124:127]
	v_mfma_f32_16x16x32_bf16 v[120:123], v[136:139], v[196:199], v[120:123]
	v_mfma_f32_16x16x32_bf16 v[108:111], v[128:131], v[214:217], v[108:111]
	v_mfma_f32_16x16x32_bf16 v[104:107], v[136:139], v[214:217], v[104:107]
	v_mfma_f32_16x16x32_bf16 v[92:95], v[128:131], v[224:227], v[92:95]
	v_mfma_f32_16x16x32_bf16 v[88:91], v[136:139], v[224:227], v[88:91]
	v_mfma_f32_16x16x32_bf16 v[76:79], v[128:131], v[232:235], v[76:79]
	v_mfma_f32_16x16x32_bf16 v[72:75], v[136:139], v[232:235], v[72:75]
	v_mfma_f32_16x16x32_bf16 v[124:127], v[132:135], v[210:213], v[124:127]
	v_mfma_f32_16x16x32_bf16 v[120:123], v[140:143], v[210:213], v[120:123]
	v_mfma_f32_16x16x32_bf16 v[108:111], v[132:135], v[218:221], v[108:111]
	v_mfma_f32_16x16x32_bf16 v[104:107], v[140:143], v[218:221], v[104:107]
	v_mfma_f32_16x16x32_bf16 v[92:95], v[132:135], v[228:231], v[92:95]
	v_mfma_f32_16x16x32_bf16 v[88:91], v[140:143], v[228:231], v[88:91]
	v_mfma_f32_16x16x32_bf16 v[76:79], v[132:135], v[236:239], v[76:79]
	v_mfma_f32_16x16x32_bf16 v[72:75], v[140:143], v[236:239], v[72:75]
	s_setprio 0
	s_setprio 1
	v_mfma_f32_16x16x32_bf16 v[116:119], v[174:177], v[196:199], v[116:119]
	v_mfma_f32_16x16x32_bf16 v[112:115], v[188:191], v[196:199], v[112:115]
	v_mfma_f32_16x16x32_bf16 v[100:103], v[174:177], v[214:217], v[100:103]
	v_mfma_f32_16x16x32_bf16 v[96:99], v[188:191], v[214:217], v[96:99]
	v_mfma_f32_16x16x32_bf16 v[84:87], v[174:177], v[224:227], v[84:87]
	v_mfma_f32_16x16x32_bf16 v[80:83], v[188:191], v[224:227], v[80:83]
	v_mfma_f32_16x16x32_bf16 v[68:71], v[174:177], v[232:235], v[68:71]
	v_mfma_f32_16x16x32_bf16 v[64:67], v[188:191], v[232:235], v[64:67]
	v_mfma_f32_16x16x32_bf16 v[116:119], v[184:187], v[210:213], v[116:119]
	v_mfma_f32_16x16x32_bf16 v[112:115], v[192:195], v[210:213], v[112:115]
	v_mfma_f32_16x16x32_bf16 v[100:103], v[184:187], v[218:221], v[100:103]
	v_mfma_f32_16x16x32_bf16 v[96:99], v[192:195], v[218:221], v[96:99]
	v_mfma_f32_16x16x32_bf16 v[84:87], v[184:187], v[228:231], v[84:87]
	v_mfma_f32_16x16x32_bf16 v[80:83], v[192:195], v[228:231], v[80:83]
	v_mfma_f32_16x16x32_bf16 v[68:71], v[184:187], v[236:239], v[68:71]
	v_mfma_f32_16x16x32_bf16 v[64:67], v[192:195], v[236:239], v[64:67]
	s_setprio 0
	s_barrier
	s_add_i32 s62, s83, s8
	v_lshl_add_u64 v[178:179], v[178:179], 0, s[22:23]
	s_mov_b32 m0, s62
	ds_read_b128 v[196:199], v183 offset:49152
	ds_read_b128 v[210:213], v183 offset:50176
	ds_read_b128 v[214:217], v183 offset:51200
	ds_read_b128 v[218:221], v183 offset:52224
	ds_read_b128 v[224:227], v183 offset:53248
	ds_read_b128 v[228:231], v183 offset:54272
	ds_read_b128 v[232:235], v183 offset:55296
	ds_read_b128 v[236:239], v183 offset:56320
	global_load_lds_dwordx4 v[178:179], off
	s_add_i32 m0, s62, 0x2000
	s_add_u32 s44, s44, 0x20080
	v_lshl_add_u64 v[178:179], v[240:241], 0, s[22:23]
	s_addc_u32 s45, s45, 0
	s_add_i32 s62, s84, s8
	global_load_lds_dwordx4 v[178:179], off
	v_lshl_add_u64 v[178:179], s[44:45], 0, v[152:153]
	s_mov_b32 m0, s62
	s_nop 0
	global_load_lds_dwordx4 v[178:179], off
	v_lshl_add_u64 v[178:179], s[44:45], 0, v[144:145]
	s_add_i32 m0, s62, 0x2000
	s_nop 0
	global_load_lds_dwordx4 v[178:179], off
	v_lshl_add_u64 v[178:179], v[242:243], 0, s[22:23]
	s_mov_b32 m0, s69
	s_nop 0
	global_load_lds_dwordx4 v[178:179], off
	v_lshl_add_u64 v[178:179], v[244:245], 0, s[22:23]
	s_mov_b32 m0, s74
	s_nop 0
	global_load_lds_dwordx4 v[178:179], off
	s_waitcnt vmcnt(8)
	s_waitcnt lgkmcnt(0)
	s_barrier
	s_setprio 1
	s_waitcnt lgkmcnt(0)
	v_mfma_f32_16x16x32_bf16 v[60:63], v[128:131], v[196:199], v[60:63]
	v_mfma_f32_16x16x32_bf16 v[56:59], v[136:139], v[196:199], v[56:59]
	v_mfma_f32_16x16x32_bf16 v[44:47], v[128:131], v[214:217], v[44:47]
	v_mfma_f32_16x16x32_bf16 v[40:43], v[136:139], v[214:217], v[40:43]
	v_mfma_f32_16x16x32_bf16 v[28:31], v[128:131], v[224:227], v[28:31]
	v_mfma_f32_16x16x32_bf16 v[24:27], v[136:139], v[224:227], v[24:27]
	v_mfma_f32_16x16x32_bf16 v[12:15], v[128:131], v[232:235], v[12:15]
	v_mfma_f32_16x16x32_bf16 v[8:11], v[136:139], v[232:235], v[8:11]
	v_mfma_f32_16x16x32_bf16 v[60:63], v[132:135], v[210:213], v[60:63]
	v_mfma_f32_16x16x32_bf16 v[56:59], v[140:143], v[210:213], v[56:59]
	v_mfma_f32_16x16x32_bf16 v[44:47], v[132:135], v[218:221], v[44:47]
	v_mfma_f32_16x16x32_bf16 v[40:43], v[140:143], v[218:221], v[40:43]
	v_mfma_f32_16x16x32_bf16 v[28:31], v[132:135], v[228:231], v[28:31]
	v_mfma_f32_16x16x32_bf16 v[24:27], v[140:143], v[228:231], v[24:27]
	v_mfma_f32_16x16x32_bf16 v[12:15], v[132:135], v[236:239], v[12:15]
	v_mfma_f32_16x16x32_bf16 v[8:11], v[140:143], v[236:239], v[8:11]
	s_setprio 0
	s_setprio 1
	v_mfma_f32_16x16x32_bf16 v[52:55], v[174:177], v[196:199], v[52:55]
	v_mfma_f32_16x16x32_bf16 v[48:51], v[188:191], v[196:199], v[48:51]
	v_mfma_f32_16x16x32_bf16 v[36:39], v[174:177], v[214:217], v[36:39]
	v_mfma_f32_16x16x32_bf16 v[32:35], v[188:191], v[214:217], v[32:35]
	v_mfma_f32_16x16x32_bf16 v[20:23], v[174:177], v[224:227], v[20:23]
	v_mfma_f32_16x16x32_bf16 v[16:19], v[188:191], v[224:227], v[16:19]
	v_mfma_f32_16x16x32_bf16 v[4:7], v[174:177], v[232:235], v[4:7]
	v_mfma_f32_16x16x32_bf16 v[0:3], v[188:191], v[232:235], v[0:3]
	v_mfma_f32_16x16x32_bf16 v[52:55], v[184:187], v[210:213], v[52:55]
	v_mfma_f32_16x16x32_bf16 v[48:51], v[192:195], v[210:213], v[48:51]
	v_mfma_f32_16x16x32_bf16 v[36:39], v[184:187], v[218:221], v[36:39]
	v_mfma_f32_16x16x32_bf16 v[32:35], v[192:195], v[218:221], v[32:35]
	v_mfma_f32_16x16x32_bf16 v[20:23], v[184:187], v[228:231], v[20:23]
	v_mfma_f32_16x16x32_bf16 v[16:19], v[192:195], v[228:231], v[16:19]
	v_mfma_f32_16x16x32_bf16 v[4:7], v[184:187], v[236:239], v[4:7]
	v_mfma_f32_16x16x32_bf16 v[0:3], v[192:195], v[236:239], v[0:3]
	s_setprio 0
	s_barrier
	s_add_i32 s82, s82, 2
	s_add_u32 s80, s80, 0x100
	s_addc_u32 s81, s81, 0
	s_add_u32 s60, s60, 0x100
	s_addc_u32 s61, s61, 0
	s_cmp_gt_u32 s82, 5
	.p2align	6

.LBB0_821:
	s_ashr_i32 s21, s20, 31
	s_lshl_b64 s[48:49], s[20:21], 19
	s_add_u32 s48, s70, s48
	s_addc_u32 s49, s71, s49
	s_and_b64 s[50:51], s[46:47], exec
	s_cselect_b32 s21, s49, s61
	s_cselect_b32 s81, s48, s60
	s_ashr_i32 s19, s18, 31
	s_lshl_b64 s[50:51], s[18:19], 19
	v_readlane_b32 s19, v254, 54
	s_add_u32 s50, s19, s50
	v_readlane_b32 s19, v254, 55
	s_addc_u32 s51, s19, s51
	s_and_b64 s[66:67], s[46:47], exec
	s_cselect_b32 s19, s51, s63
	s_cselect_b32 s82, s50, s62
	s_add_u32 s83, s62, 0x100
	s_addc_u32 s84, s63, 0
	s_add_u32 s60, s60, 0x40080
	s_addc_u32 s61, s61, 0
	s_mov_b32 s85, -2
	s_add_u32 s62, s60, 0xfffc0080
	s_addc_u32 s63, s61, -1
	s_cmp_eq_u32 s85, 12
	s_cselect_b32 s67, s21, s63
	s_cselect_b32 s66, s81, s62
	s_cselect_b32 s63, s19, s84
	s_cselect_b32 s62, s82, s83
	v_lshl_add_u64 v[198:199], s[60:61], 0, v[180:181]
	s_add_i32 m0, s68, 0xc000
	global_load_lds_dwordx4 v[198:199], off
	v_lshl_add_u64 v[198:199], s[60:61], 0, v[178:179]
	s_add_i32 m0, s68, 0xe000
	s_nop 0
	global_load_lds_dwordx4 v[198:199], off
	s_waitcnt vmcnt(8)
	s_waitcnt lgkmcnt(0)
	s_barrier
	s_setprio 1
	s_waitcnt lgkmcnt(0)
	v_mfma_f32_16x16x32_bf16 v[148:151], v[112:115], v[190:193], 0
	v_mfma_f32_16x16x32_bf16 v[144:147], v[120:123], v[190:193], 0
	v_mfma_f32_16x16x32_bf16 v[108:111], v[112:115], v[214:217], 0
	v_mfma_f32_16x16x32_bf16 v[104:107], v[120:123], v[214:217], 0
	v_mfma_f32_16x16x32_bf16 v[92:95], v[112:115], v[224:227], 0
	v_mfma_f32_16x16x32_bf16 v[88:91], v[120:123], v[224:227], 0
	v_mfma_f32_16x16x32_bf16 v[76:79], v[112:115], v[232:235], 0
	v_mfma_f32_16x16x32_bf16 v[72:75], v[120:123], v[232:235], 0
	v_mfma_f32_16x16x32_bf16 v[148:151], v[116:119], v[194:197], v[148:151]
	v_mfma_f32_16x16x32_bf16 v[144:147], v[124:127], v[194:197], v[144:147]
	v_mfma_f32_16x16x32_bf16 v[108:111], v[116:119], v[218:221], v[108:111]
	v_mfma_f32_16x16x32_bf16 v[104:107], v[124:127], v[218:221], v[104:107]
	v_mfma_f32_16x16x32_bf16 v[92:95], v[116:119], v[228:231], v[92:95]
	v_mfma_f32_16x16x32_bf16 v[88:91], v[124:127], v[228:231], v[88:91]
	v_mfma_f32_16x16x32_bf16 v[76:79], v[116:119], v[236:239], v[76:79]
	v_mfma_f32_16x16x32_bf16 v[72:75], v[124:127], v[236:239], v[72:75]
	s_setprio 0
	s_setprio 1
	v_mfma_f32_16x16x32_bf16 v[136:139], v[132:135], v[190:193], 0
	v_mfma_f32_16x16x32_bf16 v[128:131], v[182:185], v[190:193], 0
	v_mfma_f32_16x16x32_bf16 v[100:103], v[132:135], v[214:217], 0
	v_mfma_f32_16x16x32_bf16 v[96:99], v[182:185], v[214:217], 0
	v_mfma_f32_16x16x32_bf16 v[84:87], v[132:135], v[224:227], 0
	v_mfma_f32_16x16x32_bf16 v[80:83], v[182:185], v[224:227], 0
	v_mfma_f32_16x16x32_bf16 v[68:71], v[132:135], v[232:235], 0
	v_mfma_f32_16x16x32_bf16 v[64:67], v[182:185], v[232:235], 0
	v_mfma_f32_16x16x32_bf16 v[136:139], v[140:143], v[194:197], v[136:139]
	v_mfma_f32_16x16x32_bf16 v[128:131], v[186:189], v[194:197], v[128:131]
	v_mfma_f32_16x16x32_bf16 v[100:103], v[140:143], v[218:221], v[100:103]
	v_mfma_f32_16x16x32_bf16 v[96:99], v[186:189], v[218:221], v[96:99]
	v_mfma_f32_16x16x32_bf16 v[84:87], v[140:143], v[228:231], v[84:87]
	v_mfma_f32_16x16x32_bf16 v[80:83], v[186:189], v[228:231], v[80:83]
	v_mfma_f32_16x16x32_bf16 v[68:71], v[140:143], v[236:239], v[68:71]
	v_mfma_f32_16x16x32_bf16 v[64:67], v[186:189], v[236:239], v[64:67]
	s_setprio 0
	s_barrier
	s_add_i32 s86, s86, s59
	v_lshl_add_u64 v[198:199], s[62:63], 0, v[152:153]
	s_mov_b32 m0, s86
	ds_read_b128 v[190:193], v212 offset:16384
	ds_read_b128 v[194:197], v212 offset:17408
	ds_read_b128 v[214:217], v212 offset:18432
	ds_read_b128 v[218:221], v212 offset:19456
	ds_read_b128 v[224:227], v212 offset:20480
	ds_read_b128 v[228:231], v212 offset:21504
	ds_read_b128 v[232:235], v212 offset:22528
	ds_read_b128 v[236:239], v212 offset:23552
	global_load_lds_dwordx4 v[198:199], off
	s_add_i32 m0, s86, 0x2000
	s_add_u32 s86, s62, 0x40000
	v_lshl_add_u64 v[240:241], s[62:63], 0, v[172:173]
	s_addc_u32 s87, s63, 0
	s_add_i32 s89, s89, s59
	global_load_lds_dwordx4 v[240:241], off
	v_lshl_add_u64 v[242:243], s[86:87], 0, v[152:153]
	s_mov_b32 m0, s89
	v_lshl_add_u64 v[244:245], s[66:67], 0, v[174:175]
	global_load_lds_dwordx4 v[242:243], off
	v_lshl_add_u64 v[242:243], s[86:87], 0, v[172:173]
	s_add_i32 m0, s89, 0x2000
	s_nop 0
	global_load_lds_dwordx4 v[242:243], off
	v_lshl_add_u64 v[242:243], s[66:67], 0, v[176:177]
	s_mov_b32 m0, s68
	s_nop 0
	global_load_lds_dwordx4 v[242:243], off
	s_mov_b32 m0, s69
	s_nop 0
	global_load_lds_dwordx4 v[244:245], off
	s_waitcnt vmcnt(8)
	s_waitcnt lgkmcnt(0)
	s_barrier
	s_setprio 1
	s_waitcnt lgkmcnt(0)
	v_mfma_f32_16x16x32_bf16 v[60:63], v[112:115], v[190:193], 0
	v_mfma_f32_16x16x32_bf16 v[56:59], v[120:123], v[190:193], 0
	v_mfma_f32_16x16x32_bf16 v[44:47], v[112:115], v[214:217], 0
	v_mfma_f32_16x16x32_bf16 v[40:43], v[120:123], v[214:217], 0
	v_mfma_f32_16x16x32_bf16 v[28:31], v[112:115], v[224:227], 0
	v_mfma_f32_16x16x32_bf16 v[24:27], v[120:123], v[224:227], 0
	v_mfma_f32_16x16x32_bf16 v[12:15], v[112:115], v[232:235], 0
	v_mfma_f32_16x16x32_bf16 v[8:11], v[120:123], v[232:235], 0
	v_mfma_f32_16x16x32_bf16 v[60:63], v[116:119], v[194:197], v[60:63]
	v_mfma_f32_16x16x32_bf16 v[56:59], v[124:127], v[194:197], v[56:59]
	v_mfma_f32_16x16x32_bf16 v[44:47], v[116:119], v[218:221], v[44:47]
	v_mfma_f32_16x16x32_bf16 v[40:43], v[124:127], v[218:221], v[40:43]
	v_mfma_f32_16x16x32_bf16 v[28:31], v[116:119], v[228:231], v[28:31]
	v_mfma_f32_16x16x32_bf16 v[24:27], v[124:127], v[228:231], v[24:27]
	v_mfma_f32_16x16x32_bf16 v[12:15], v[116:119], v[236:239], v[12:15]
	v_mfma_f32_16x16x32_bf16 v[8:11], v[124:127], v[236:239], v[8:11]
	s_setprio 0
	s_setprio 1
	v_mfma_f32_16x16x32_bf16 v[52:55], v[132:135], v[190:193], 0
	v_mfma_f32_16x16x32_bf16 v[48:51], v[182:185], v[190:193], 0
	v_mfma_f32_16x16x32_bf16 v[36:39], v[132:135], v[214:217], 0
	v_mfma_f32_16x16x32_bf16 v[32:35], v[182:185], v[214:217], 0
	v_mfma_f32_16x16x32_bf16 v[20:23], v[132:135], v[224:227], 0
	v_mfma_f32_16x16x32_bf16 v[16:19], v[182:185], v[224:227], 0
	v_mfma_f32_16x16x32_bf16 v[4:7], v[132:135], v[232:235], 0
	v_mfma_f32_16x16x32_bf16 v[0:3], v[182:185], v[232:235], 0
	v_mfma_f32_16x16x32_bf16 v[52:55], v[140:143], v[194:197], v[52:55]
	v_mfma_f32_16x16x32_bf16 v[48:51], v[186:189], v[194:197], v[48:51]
	v_mfma_f32_16x16x32_bf16 v[36:39], v[140:143], v[218:221], v[36:39]
	v_mfma_f32_16x16x32_bf16 v[32:35], v[186:189], v[218:221], v[32:35]
	v_mfma_f32_16x16x32_bf16 v[20:23], v[140:143], v[228:231], v[20:23]
	v_mfma_f32_16x16x32_bf16 v[16:19], v[186:189], v[228:231], v[16:19]
	v_mfma_f32_16x16x32_bf16 v[4:7], v[140:143], v[236:239], v[4:7]
	v_mfma_f32_16x16x32_bf16 v[0:3], v[186:189], v[236:239], v[0:3]
	s_setprio 0
	s_barrier
	s_add_i32 s86, 0, 0x18000
	s_add_i32 s87, 0, 0x1c000
	v_add_u32_e32 v124, s86, v210
	v_add_u32_e32 v186, s87, v210
	ds_read_b128 v[112:115], v124
	ds_read_b128 v[116:119], v124 offset:1024
	ds_read_b128 v[120:123], v124 offset:2048
	ds_read_b128 v[124:127], v124 offset:3072
	ds_read_b128 v[132:135], v186
	ds_read_b128 v[140:143], v186 offset:1024
	ds_read_b128 v[182:185], v186 offset:2048
	ds_read_b128 v[186:189], v186 offset:3072
	s_add_u32 s66, s66, 0x40000
	s_addc_u32 s67, s67, 0
	s_mov_b32 m0, s74
	v_lshl_add_u64 v[246:247], s[66:67], 0, v[176:177]
	ds_read_b128 v[190:193], v212 offset:32768
	ds_read_b128 v[194:197], v212 offset:33792
	ds_read_b128 v[214:217], v212 offset:34816
	ds_read_b128 v[218:221], v212 offset:35840
	ds_read_b128 v[224:227], v212 offset:36864
	ds_read_b128 v[228:231], v212 offset:37888
	ds_read_b128 v[232:235], v212 offset:38912
	ds_read_b128 v[236:239], v212 offset:39936
	global_load_lds_dwordx4 v[246:247], off
	v_lshl_add_u64 v[246:247], s[66:67], 0, v[174:175]
	s_mov_b32 m0, s75
	s_nop 0
	global_load_lds_dwordx4 v[246:247], off
	s_waitcnt vmcnt(8)
	s_waitcnt lgkmcnt(0)
	s_barrier
	s_setprio 1
	s_waitcnt lgkmcnt(0)
	v_mfma_f32_16x16x32_bf16 v[148:151], v[112:115], v[190:193], v[148:151]
	v_mfma_f32_16x16x32_bf16 v[144:147], v[120:123], v[190:193], v[144:147]
	v_mfma_f32_16x16x32_bf16 v[108:111], v[112:115], v[214:217], v[108:111]
	v_mfma_f32_16x16x32_bf16 v[104:107], v[120:123], v[214:217], v[104:107]
	v_mfma_f32_16x16x32_bf16 v[92:95], v[112:115], v[224:227], v[92:95]
	v_mfma_f32_16x16x32_bf16 v[88:91], v[120:123], v[224:227], v[88:91]
	v_mfma_f32_16x16x32_bf16 v[76:79], v[112:115], v[232:235], v[76:79]
	v_mfma_f32_16x16x32_bf16 v[72:75], v[120:123], v[232:235], v[72:75]
	v_mfma_f32_16x16x32_bf16 v[148:151], v[116:119], v[194:197], v[148:151]
	v_mfma_f32_16x16x32_bf16 v[144:147], v[124:127], v[194:197], v[144:147]
	v_mfma_f32_16x16x32_bf16 v[108:111], v[116:119], v[218:221], v[108:111]
	v_mfma_f32_16x16x32_bf16 v[104:107], v[124:127], v[218:221], v[104:107]
	v_mfma_f32_16x16x32_bf16 v[92:95], v[116:119], v[228:231], v[92:95]
	v_mfma_f32_16x16x32_bf16 v[88:91], v[124:127], v[228:231], v[88:91]
	v_mfma_f32_16x16x32_bf16 v[76:79], v[116:119], v[236:239], v[76:79]
	v_mfma_f32_16x16x32_bf16 v[72:75], v[124:127], v[236:239], v[72:75]
	s_setprio 0
	s_setprio 1
	v_mfma_f32_16x16x32_bf16 v[136:139], v[132:135], v[190:193], v[136:139]
	v_mfma_f32_16x16x32_bf16 v[128:131], v[182:185], v[190:193], v[128:131]
	v_mfma_f32_16x16x32_bf16 v[100:103], v[132:135], v[214:217], v[100:103]
	v_mfma_f32_16x16x32_bf16 v[96:99], v[182:185], v[214:217], v[96:99]
	v_mfma_f32_16x16x32_bf16 v[84:87], v[132:135], v[224:227], v[84:87]
	v_mfma_f32_16x16x32_bf16 v[80:83], v[182:185], v[224:227], v[80:83]
	v_mfma_f32_16x16x32_bf16 v[68:71], v[132:135], v[232:235], v[68:71]
	v_mfma_f32_16x16x32_bf16 v[64:67], v[182:185], v[232:235], v[64:67]
	v_mfma_f32_16x16x32_bf16 v[136:139], v[140:143], v[194:197], v[136:139]
	v_mfma_f32_16x16x32_bf16 v[128:131], v[186:189], v[194:197], v[128:131]
	v_mfma_f32_16x16x32_bf16 v[100:103], v[140:143], v[218:221], v[100:103]
	v_mfma_f32_16x16x32_bf16 v[96:99], v[186:189], v[218:221], v[96:99]
	v_mfma_f32_16x16x32_bf16 v[84:87], v[140:143], v[228:231], v[84:87]
	v_mfma_f32_16x16x32_bf16 v[80:83], v[186:189], v[228:231], v[80:83]
	v_mfma_f32_16x16x32_bf16 v[68:71], v[140:143], v[236:239], v[68:71]
	v_mfma_f32_16x16x32_bf16 v[64:67], v[186:189], v[236:239], v[64:67]
	s_setprio 0
	s_barrier
	s_add_i32 s66, s86, s59
	v_lshl_add_u64 v[198:199], v[198:199], 0, s[22:23]
	s_mov_b32 m0, s66
	ds_read_b128 v[190:193], v212 offset:49152
	ds_read_b128 v[194:197], v212 offset:50176
	ds_read_b128 v[214:217], v212 offset:51200
	ds_read_b128 v[218:221], v212 offset:52224
	ds_read_b128 v[224:227], v212 offset:53248
	ds_read_b128 v[228:231], v212 offset:54272
	ds_read_b128 v[232:235], v212 offset:55296
	ds_read_b128 v[236:239], v212 offset:56320
	global_load_lds_dwordx4 v[198:199], off
	s_add_i32 m0, s66, 0x2000
	s_add_u32 s62, s62, 0x40080
	v_lshl_add_u64 v[198:199], v[240:241], 0, s[22:23]
	s_addc_u32 s63, s63, 0
	s_add_i32 s66, s87, s59
	global_load_lds_dwordx4 v[198:199], off
	v_lshl_add_u64 v[198:199], s[62:63], 0, v[152:153]
	s_mov_b32 m0, s66
	s_nop 0
	global_load_lds_dwordx4 v[198:199], off
	v_lshl_add_u64 v[198:199], s[62:63], 0, v[172:173]
	s_add_i32 m0, s66, 0x2000
	s_nop 0
	global_load_lds_dwordx4 v[198:199], off
	v_lshl_add_u64 v[198:199], v[242:243], 0, s[22:23]
	s_mov_b32 m0, s77
	s_nop 0
	global_load_lds_dwordx4 v[198:199], off
	v_lshl_add_u64 v[198:199], v[244:245], 0, s[22:23]
	s_mov_b32 m0, s78
	s_nop 0
	global_load_lds_dwordx4 v[198:199], off
	s_waitcnt vmcnt(8)
	s_waitcnt lgkmcnt(0)
	s_barrier
	s_setprio 1
	s_waitcnt lgkmcnt(0)
	v_mfma_f32_16x16x32_bf16 v[60:63], v[112:115], v[190:193], v[60:63]
	v_mfma_f32_16x16x32_bf16 v[56:59], v[120:123], v[190:193], v[56:59]
	v_mfma_f32_16x16x32_bf16 v[44:47], v[112:115], v[214:217], v[44:47]
	v_mfma_f32_16x16x32_bf16 v[40:43], v[120:123], v[214:217], v[40:43]
	v_mfma_f32_16x16x32_bf16 v[28:31], v[112:115], v[224:227], v[28:31]
	v_mfma_f32_16x16x32_bf16 v[24:27], v[120:123], v[224:227], v[24:27]
	v_mfma_f32_16x16x32_bf16 v[12:15], v[112:115], v[232:235], v[12:15]
	v_mfma_f32_16x16x32_bf16 v[8:11], v[120:123], v[232:235], v[8:11]
	v_mfma_f32_16x16x32_bf16 v[60:63], v[116:119], v[194:197], v[60:63]
	v_mfma_f32_16x16x32_bf16 v[56:59], v[124:127], v[194:197], v[56:59]
	v_mfma_f32_16x16x32_bf16 v[44:47], v[116:119], v[218:221], v[44:47]
	v_mfma_f32_16x16x32_bf16 v[40:43], v[124:127], v[218:221], v[40:43]
	v_mfma_f32_16x16x32_bf16 v[28:31], v[116:119], v[228:231], v[28:31]
	v_mfma_f32_16x16x32_bf16 v[24:27], v[124:127], v[228:231], v[24:27]
	v_mfma_f32_16x16x32_bf16 v[12:15], v[116:119], v[236:239], v[12:15]
	v_mfma_f32_16x16x32_bf16 v[8:11], v[124:127], v[236:239], v[8:11]
	s_setprio 0
	s_setprio 1
	v_mfma_f32_16x16x32_bf16 v[52:55], v[132:135], v[190:193], v[52:55]
	v_mfma_f32_16x16x32_bf16 v[48:51], v[182:185], v[190:193], v[48:51]
	v_mfma_f32_16x16x32_bf16 v[36:39], v[132:135], v[214:217], v[36:39]
	v_mfma_f32_16x16x32_bf16 v[32:35], v[182:185], v[214:217], v[32:35]
	v_mfma_f32_16x16x32_bf16 v[20:23], v[132:135], v[224:227], v[20:23]
	v_mfma_f32_16x16x32_bf16 v[16:19], v[182:185], v[224:227], v[16:19]
	v_mfma_f32_16x16x32_bf16 v[4:7], v[132:135], v[232:235], v[4:7]
	v_mfma_f32_16x16x32_bf16 v[0:3], v[182:185], v[232:235], v[0:3]
	v_mfma_f32_16x16x32_bf16 v[52:55], v[140:143], v[194:197], v[52:55]
	v_mfma_f32_16x16x32_bf16 v[48:51], v[186:189], v[194:197], v[48:51]
	v_mfma_f32_16x16x32_bf16 v[36:39], v[140:143], v[218:221], v[36:39]
	v_mfma_f32_16x16x32_bf16 v[32:35], v[186:189], v[218:221], v[32:35]
	v_mfma_f32_16x16x32_bf16 v[20:23], v[140:143], v[228:231], v[20:23]
	v_mfma_f32_16x16x32_bf16 v[16:19], v[186:189], v[228:231], v[16:19]
	v_mfma_f32_16x16x32_bf16 v[4:7], v[140:143], v[236:239], v[4:7]
	v_mfma_f32_16x16x32_bf16 v[0:3], v[186:189], v[236:239], v[0:3]
	s_setprio 0
	s_barrier
	s_add_i32 s85, s85, 2
	s_add_u32 s83, s83, 0x100
	s_addc_u32 s84, s84, 0
	s_add_u32 s60, s60, 0x100
	s_addc_u32 s61, s61, 0
	s_cmp_gt_u32 s85, 13
	.p2align	6
